# P0: odd workgroups build their S5 table item after the streaming conversion parts; scan: dropped redundant store-drain wait; S5 Toeplitz blocks 0-1: ds_reads issued 5 ahead into a rotating register po
# speedup vs baseline: 1.0151x; 1.0033x over previous
.LBB0_7:
	s_load_dwordx16 s[36:51], s[0:1], 0x0
	s_load_dwordx4 s[12:15], s[0:1], 0x100
	s_load_dwordx16 s[52:67], s[0:1], 0xc0
	s_mov_b32 s21, 0
	v_mov_b32_e32 v139, 0
	s_waitcnt lgkmcnt(0)
	s_mov_b32 s92, s50
	s_add_u32 s2, s12, 0x12500000
	s_addc_u32 s3, s13, 0
	v_writelane_b32 v250, s2, 10
	s_lshl_b32 s22, s26, 3
	s_mov_b32 s95, s51
	v_writelane_b32 v250, s3, 11
	s_mov_b32 s84, s50
	v_readlane_b32 s10, v250, 2
	s_lshl_b32 s14, s10, 3
	s_add_u32 s2, s12, 0xfd00000
	v_writelane_b32 v250, s2, 12
	s_addc_u32 s2, s13, 0
	s_cmpk_lt_i32 s10, 0x100
	v_writelane_b32 v250, s2, 13
	s_cselect_b64 s[2:3], -1, 0
	v_writelane_b32 v250, s2, 14
	v_mov_b32_e32 v223, 0x358637bd
	v_mov_b32_e32 v224, 0x260
	v_writelane_b32 v250, s3, 15
	s_add_u32 s2, s12, 0x3b00000
	v_writelane_b32 v250, s2, 16
	s_addc_u32 s2, s13, 0
	v_writelane_b32 v250, s2, 17
	s_lshl_b32 s2, s10, 9
	v_writelane_b32 v250, s2, 18
	s_add_u32 s2, s12, 0x12c00000
	s_addc_u32 s3, s13, 0
	v_writelane_b32 v250, s2, 19
	s_lshl_b32 s24, s26, 9
	s_mov_b32 s25, s24
	v_writelane_b32 v250, s3, 20
	s_add_u32 s2, s12, 0x12a00000
	v_writelane_b32 v250, s2, 21
	s_addc_u32 s2, s13, 0
	v_writelane_b32 v250, s2, 22
	s_add_u32 s2, s12, 0x2b00000
	v_writelane_b32 v250, s2, 23
	s_addc_u32 s2, s13, 0
	v_writelane_b32 v250, s2, 24
	s_add_u32 s2, s12, 0x100000
	v_writelane_b32 v250, s2, 25
	s_addc_u32 s2, s13, 0
	s_cmp_lg_u64 s[38:39], 0
	v_writelane_b32 v250, s2, 26
	s_cselect_b64 s[2:3], -1, 0
	s_lshl_b32 s28, s26, 5
	v_writelane_b32 v250, s2, 27
	s_cmpk_lt_i32 s10, 0xca
	v_cvt_f32_u32_e32 v1, s24
	v_writelane_b32 v250, s3, 28
	s_cselect_b64 s[2:3], -1, 0
	v_writelane_b32 v250, s2, 29
	v_rcp_iflag_f32_e32 v1, v1
	v_mov_b32_e32 v225, 0x3c0881c4
	v_writelane_b32 v250, s3, 30
	s_add_u32 s2, s12, 0x12100000
	s_addc_u32 s3, s13, 0
	v_writelane_b32 v250, s2, 31
	v_mul_f32_e32 v1, 0x4f7ffffe, v1
	v_cvt_u32_f32_e32 v1, v1
	v_writelane_b32 v250, s3, 32
	s_add_u32 s2, s12, 0x12200000
	v_writelane_b32 v250, s2, 33
	s_addc_u32 s2, s13, 0
	v_writelane_b32 v250, s2, 34
	s_add_u32 s2, s12, 0x11d00000
	s_addc_u32 s3, s13, 0
	v_writelane_b32 v250, s2, 35
	v_mov_b32_e32 v226, 0xbab64f3b
	v_mov_b32_e32 v227, 1
	v_writelane_b32 v250, s3, 36
	s_add_u32 s2, s12, 0x12300000
	s_addc_u32 s3, s13, 0
	v_writelane_b32 v250, s2, 37
	v_mov_b64_e32 v[248:249], 0xff
	v_mov_b32_e32 v229, 0x3f80
	v_writelane_b32 v250, s3, 38
	s_add_u32 s2, s12, 0x12400000
	s_addc_u32 s3, s13, 0
	v_writelane_b32 v250, s2, 39
	v_mov_b32_e32 v4, v139
	v_mov_b32_e32 v5, v139
	v_writelane_b32 v250, s3, 40
	s_add_u32 s2, s66, 0x2000000
	s_addc_u32 s3, s67, 0
	s_add_u32 s30, s12, 0x4b00000
	v_writelane_b32 v250, s2, 41
	s_addc_u32 s31, s13, 0
	v_mov_b32_e32 v230, 2
	v_writelane_b32 v250, s3, 42
	s_add_u32 s2, s12, 0xeb00000
	s_addc_u32 s3, s13, 0
	v_writelane_b32 v250, s2, 43
	v_mov_b32_e32 v231, 0x7f800000
	v_mov_b32_e32 v232, 0x7e0
	v_writelane_b32 v250, s3, 44
	s_add_u32 s2, s12, 0xed00000
	v_writelane_b32 v250, s2, 45
	s_addc_u32 s2, s13, 0
	v_writelane_b32 v250, s2, 46
	s_add_u32 s2, s12, 0xeb00040
	s_addc_u32 s3, s13, 0
	v_writelane_b32 v250, s2, 47
	v_mov_b64_e32 v[144:145], 0x4ff
	v_not_b32_e32 v233, 63
	v_writelane_b32 v250, s3, 48
	v_not_b32_e32 v234, 31
	v_readlane_b32 s7, v250, 3
	s_cmpk_lt_i32 s7, 0x100
	s_cselect_b64 s[2:3], -1, 0
	v_writelane_b32 v250, s2, 49
	s_ashr_i32 s5, s26, 31
	v_mov_b32_e32 v235, 0x7fc00000
	v_writelane_b32 v250, s3, 50
	s_ashr_i32 s2, s7, 31
	v_writelane_b32 v250, s2, 51
	s_lshr_b32 s2, s2, 29
	s_add_i32 s2, s7, s2
	s_ashr_i32 s3, s2, 3
	s_and_b32 s2, s2, -8
	s_sub_i32 s2, s7, s2
	s_lshl_b32 s4, s2, 5
	s_cmpk_lt_i32 s7, 0x500
	v_writelane_b32 v250, s5, 52
	s_cselect_b64 s[8:9], -1, 0
	v_writelane_b32 v250, s8, 53
	s_cmpk_gt_i32 s7, 0x4ff
	s_movk_i32 s69, 0x4000
	v_writelane_b32 v250, s9, 54
	s_cselect_b64 s[8:9], -1, 0
	v_writelane_b32 v250, s8, 55
	s_mov_b32 s33, 0xffff0000
	s_movk_i32 s97, 0x1ff
	v_writelane_b32 v250, s9, 56
	s_add_u32 s8, s12, 0x200
	s_addc_u32 s9, s13, 0
	v_writelane_b32 v250, s8, 57
	s_movk_i32 s68, 0x2000
	s_mov_b32 s19, 0x8000
	v_writelane_b32 v250, s9, 58
	s_add_u32 s8, s12, 0x1000
	s_addc_u32 s9, s13, 0
	v_writelane_b32 v250, s8, 59
	s_mov_b32 s27, 0xc000
	s_mov_b32 s18, 0x14000
	v_writelane_b32 v250, s9, 60
	s_add_u32 s8, s12, 0x1100
	s_addc_u32 s9, s13, 0
	v_writelane_b32 v250, s8, 61
	s_mov_b32 s17, 0x1c000
	s_movk_i32 s94, 0x7fff
	v_writelane_b32 v250, s9, 62
	s_add_u32 s8, s12, 0x1200
	s_addc_u32 s9, s13, 0
	v_writelane_b32 v250, s8, 63
	s_movk_i32 s70, 0x6000
	s_mov_b32 s90, 0x1e000
	v_writelane_b32 v251, s9, 0
	s_add_u32 s8, s12, 0x1300
	s_addc_u32 s9, s13, 0
	v_writelane_b32 v251, s8, 1
	s_cmp_eq_u32 s6, 15
	s_mov_b32 s80, 0x3fb8aa3b
	v_writelane_b32 v251, s9, 2
	s_cselect_b64 s[8:9], -1, 0
	v_writelane_b32 v251, s8, 3
	s_cmp_eq_u32 s6, 14
	s_movk_i32 s71, 0x1f8
	v_writelane_b32 v251, s9, 4
	s_cselect_b64 s[8:9], -1, 0
	v_writelane_b32 v251, s8, 5
	s_cmp_eq_u32 s6, 13
	s_mov_b32 s81, 0xc2ce8ed0
	v_writelane_b32 v251, s9, 6
	s_cselect_b64 s[8:9], -1, 0
	v_writelane_b32 v251, s8, 7
	s_cmp_eq_u32 s6, 12
	s_mov_b32 s82, 0x42b17218
	v_writelane_b32 v251, s9, 8
	s_cselect_b64 s[8:9], -1, 0
	v_writelane_b32 v251, s8, 9
	s_cmp_eq_u32 s6, 11
	s_brev_b32 s83, 18
	v_writelane_b32 v251, s9, 10
	s_cselect_b64 s[8:9], -1, 0
	v_writelane_b32 v251, s8, 11
	s_cmp_eq_u32 s6, 10
	s_mov_b32 s76, 0xfe5163ab
	v_writelane_b32 v251, s9, 12
	s_cselect_b64 s[8:9], -1, 0
	v_writelane_b32 v251, s8, 13
	s_cmp_eq_u32 s6, 9
	s_mov_b32 s77, 0x3c439041
	v_writelane_b32 v251, s9, 14
	s_cselect_b64 s[8:9], -1, 0
	v_writelane_b32 v251, s8, 15
	s_cmp_eq_u32 s6, 8
	s_mov_b32 s78, 0xdb629599
	v_writelane_b32 v251, s9, 16
	s_cselect_b64 s[8:9], -1, 0
	v_writelane_b32 v251, s8, 17
	s_cmp_eq_u32 s6, 7
	s_mov_b32 s79, 0xf534ddc0
	v_writelane_b32 v251, s9, 18
	s_cselect_b64 s[8:9], -1, 0
	v_writelane_b32 v251, s8, 19
	s_cmp_eq_u32 s6, 6
	s_mov_b32 s72, 0xfc2757d1
	v_writelane_b32 v251, s9, 20
	s_cselect_b64 s[8:9], -1, 0
	v_writelane_b32 v251, s8, 21
	s_cmp_eq_u32 s6, 5
	s_mov_b32 s73, 0x4e441529
	v_writelane_b32 v251, s9, 22
	s_cselect_b64 s[8:9], -1, 0
	v_writelane_b32 v251, s8, 23
	s_cmp_eq_u32 s6, 4
	s_mov_b32 s74, 0xa2f9836e
	v_writelane_b32 v251, s9, 24
	s_cselect_b64 s[8:9], -1, 0
	v_writelane_b32 v251, s8, 25
	s_cmp_eq_u32 s6, 3
	s_mov_b32 s75, 0x3fc90fda
	v_writelane_b32 v251, s9, 26
	s_cselect_b64 s[8:9], -1, 0
	v_writelane_b32 v251, s8, 27
	s_cmp_eq_u32 s6, 2
	s_mov_b32 s91, 0x20000
	v_writelane_b32 v251, s9, 28
	s_cselect_b64 s[8:9], -1, 0
	v_writelane_b32 v251, s8, 29
	s_cmp_eq_u32 s6, 1
	s_nop 0
	v_writelane_b32 v251, s9, 30
	s_cselect_b64 s[8:9], -1, 0
	v_writelane_b32 v251, s8, 31
	s_cmp_eq_u32 s6, 0
	s_nop 0
	v_writelane_b32 v251, s9, 32
	s_cselect_b64 s[8:9], -1, 0
	s_lshl_b32 s5, s6, 8
	s_add_u32 s5, s12, s5
	v_writelane_b32 v251, s8, 33
	s_addc_u32 s6, s13, 0
	s_nop 0
	v_writelane_b32 v251, s9, 34
	s_add_u32 s8, s5, 0x1400
	s_addc_u32 s9, s6, 0
	v_writelane_b32 v251, s8, 35
	s_nop 1
	v_writelane_b32 v251, s9, 36
	s_add_u32 s8, s5, 0x2400
	s_addc_u32 s9, s6, 0
	v_writelane_b32 v251, s8, 37
	s_add_u32 s6, s12, 0x3400
	s_addc_u32 s7, s13, 0
	v_writelane_b32 v251, s9, 38
	v_writelane_b32 v251, s6, 39
	s_mul_i32 s5, s2, 33
	s_nop 0
	v_writelane_b32 v251, s7, 40
	s_add_u32 s6, s12, 0x3500
	s_addc_u32 s7, s13, 0
	s_cmp_lt_i32 s2, 0
	s_cselect_b32 s4, s5, s4
	s_movk_i32 s5, 0xa1
	v_writelane_b32 v251, s6, 41
	s_cselect_b32 s5, s5, 0xa0
	s_add_i32 s4, s4, s3
	v_writelane_b32 v251, s7, 42
	s_ashr_i32 s6, s4, 31
	s_lshr_b32 s6, s6, 27
	s_add_i32 s6, s4, s6
	s_and_b32 s7, s6, 0xffe0
	s_sub_i32 s4, s4, s7
	s_bfe_i32 s7, s4, 0x80000
	s_bfe_u32 s7, s7, 0x3000c
	s_add_i32 s7, s4, s7
	s_and_b32 s8, s7, 0xf8
	s_mul_i32 s2, s2, s5
	s_sub_i32 s4, s4, s8
	s_ashr_i32 s6, s6, 5
	s_add_i32 s2, s2, s3
	s_lshl_b32 s6, s6, 3
	s_sext_i32_i8 s4, s4
	s_mul_hi_i32 s3, s2, 0x66666667
	s_add_i32 s11, s6, s4
	s_lshr_b32 s4, s3, 31
	s_ashr_i32 s3, s3, 6
	s_add_i32 s3, s3, s4
	s_mul_i32 s4, s3, 0xa0
	s_sub_i32 s4, s2, s4
	s_bfe_i32 s2, s7, 0x80000
	s_lshl_b32 s6, s3, 3
	s_sext_i32_i16 s5, s2
	s_sub_i32 s2, 64, s6
	s_min_i32 s7, s2, 8
	s_bfe_u32 s2, s4, 0x3001c
	s_add_i32 s2, s4, s2
	s_sext_i32_i16 s8, s2
	s_and_b32 s2, s2, 0xfff8
	s_sub_i32 s2, s4, s2
	s_sext_i32_i16 s9, s2
	s_mov_b32 s3, -1
	s_mov_b32 s2, s21
	s_and_b64 s[2:3], s[24:25], s[2:3]
	v_writelane_b32 v251, s2, 43
	s_ashr_i32 s15, s5, 3
	s_nop 0
	v_writelane_b32 v251, s3, 44
	s_lshr_b32 s2, s5, 3
	s_bfe_i64 s[2:3], s[2:3], 0x100000
	s_lshl_b64 s[2:3], s[2:3], 20
	v_writelane_b32 v251, s2, 45
	s_lshl_b32 s5, s11, 8
	s_nop 0
	v_writelane_b32 v251, s3, 46
	s_add_i32 s2, s6, s9
	v_writelane_b32 v251, s2, 47
	s_nop 1
	v_writelane_b32 v251, s3, 48
	s_ashr_i32 s2, s8, 3
	v_writelane_b32 v251, s2, 49
	s_lshl_b32 s8, s26, 10
	s_mov_b32 s86, s8
	v_writelane_b32 v251, s3, 50
	v_writelane_b32 v251, s11, 51
	v_writelane_b32 v251, s5, 52
	v_writelane_b32 v251, s15, 53
	s_lshl_b32 s5, s15, 8
	s_mul_i32 s3, s11, 0x280000
	v_writelane_b32 v251, s5, 54
	s_mul_hi_i32 s2, s11, 0x280000
	s_add_u32 s34, s30, s3
	v_writelane_b32 v251, s30, 55
	s_addc_u32 s35, s31, s2
	s_add_u32 s2, s34, 0x140000
	v_writelane_b32 v251, s31, 56
	v_writelane_b32 v251, s34, 57
	s_addc_u32 s3, s35, 0
	s_nop 0
	v_writelane_b32 v251, s35, 58
	v_writelane_b32 v251, s2, 59
	s_nop 1
	v_writelane_b32 v251, s3, 60
	s_sub_i32 s2, 0, s24
	v_mul_lo_u32 v2, s2, v1
	s_abs_i32 s2, s7
	v_cvt_f32_u32_e32 v3, s2
	s_sub_i32 s3, 0, s2
	v_mul_hi_u32 v2, v1, v2
	v_add_u32_e32 v222, v1, v2
	v_rcp_iflag_f32_e32 v3, v3
	v_mov_b32_e32 v2, v139
	v_mbcnt_lo_u32_b32 v1, -1, 0
	v_mbcnt_hi_u32_b32 v228, -1, v1
	v_mul_f32_e32 v3, 0x4f7ffffe, v3
	v_cvt_u32_f32_e32 v3, v3
	s_nop 0
	v_readfirstlane_b32 s5, v3
	s_mul_i32 s3, s3, s5
	s_mul_hi_u32 s3, s5, s3
	s_add_i32 s5, s5, s3
	s_abs_i32 s3, s4
	s_mul_hi_u32 s5, s3, s5
	s_mul_i32 s5, s5, s2
	s_sub_i32 s3, s3, s5
	s_ashr_i32 s4, s4, 31
	s_sub_i32 s5, s3, s2
	s_cmp_ge_u32 s3, s2
	s_cselect_b32 s3, s5, s3
	s_sub_i32 s5, s3, s2
	s_cmp_ge_u32 s3, s2
	s_cselect_b32 s2, s5, s3
	s_xor_b32 s2, s2, s4
	s_sub_i32 s2, s2, s4
	s_add_i32 s2, s6, s2
	s_ashr_i32 s23, s22, 31
	v_writelane_b32 v251, s2, 61
	s_lshl_b64 s[2:3], s[22:23], 6
	s_ashr_i32 s15, s14, 31
	v_writelane_b32 v251, s2, 62
	v_mov_b32_e32 v3, v139
	s_nop 0
	v_writelane_b32 v251, s3, 63
	s_add_u32 s2, s66, 0xc00
	v_writelane_b32 v252, s52, 0
	s_addc_u32 s3, s67, 0
	s_ashr_i32 s29, s28, 31
	v_writelane_b32 v252, s53, 1
	v_writelane_b32 v252, s54, 2
	v_writelane_b32 v252, s55, 3
	v_writelane_b32 v252, s56, 4
	v_writelane_b32 v252, s57, 5
	v_writelane_b32 v252, s58, 6
	v_writelane_b32 v252, s59, 7
	v_writelane_b32 v252, s60, 8
	v_writelane_b32 v252, s61, 9
	v_writelane_b32 v252, s62, 10
	v_writelane_b32 v252, s63, 11
	v_writelane_b32 v252, s64, 12
	v_writelane_b32 v252, s65, 13
	v_writelane_b32 v252, s66, 14
	v_writelane_b32 v252, s67, 15
	v_writelane_b32 v252, s2, 16
	s_ashr_i32 s25, s24, 31
	s_lshl_b32 s87, s26, 15
	v_writelane_b32 v252, s3, 17
	s_mov_b32 s2, s46
	v_writelane_b32 v252, s2, 18
	s_mov_b32 s2, s47
	v_writelane_b32 v252, s2, 19
	s_mov_b32 s2, s46
	v_writelane_b32 v252, s2, 20
	s_mov_b32 s2, s47
	v_writelane_b32 v252, s2, 21
	v_writelane_b32 v252, s36, 22
	s_lshl_b32 s2, s10, 8
	s_lshl_b32 s96, s26, 8
	v_writelane_b32 v252, s37, 23
	v_writelane_b32 v252, s38, 24
	v_writelane_b32 v252, s39, 25
	v_writelane_b32 v252, s40, 26
	v_writelane_b32 v252, s41, 27
	v_writelane_b32 v252, s42, 28
	v_writelane_b32 v252, s43, 29
	v_writelane_b32 v252, s44, 30
	v_writelane_b32 v252, s45, 31
	v_writelane_b32 v252, s46, 32
	v_writelane_b32 v252, s47, 33
	v_writelane_b32 v252, s48, 34
	v_writelane_b32 v252, s49, 35
	v_writelane_b32 v252, s50, 36
	v_writelane_b32 v252, s51, 37
	v_writelane_b32 v252, s8, 38
	v_writelane_b32 v252, s2, 39
	s_lshl_b32 s2, s26, 4
	v_writelane_b32 v252, s2, 40
	v_writelane_b32 v252, s14, 41
	s_add_i32 s2, s14, s22
	s_lshl_b64 s[4:5], s[24:25], 1
	v_writelane_b32 v252, s15, 42
	v_writelane_b32 v252, s2, 43
	s_lshl_b32 s2, s10, 6
	s_or_b32 s3, s2, 48
	v_writelane_b32 v252, s3, 44
	s_lshl_b32 s3, s26, 6
	v_writelane_b32 v252, s3, 45
	s_or_b32 s3, s2, 32
	v_writelane_b32 v252, s3, 46
	v_writelane_b32 v252, s2, 47
	s_or_b32 s2, s2, 16
	v_writelane_b32 v252, s2, 48
	s_lshl_b64 s[2:3], s[22:23], 12
	v_writelane_b32 v252, s2, 49
	s_mov_b32 s85, s51
	s_load_dwordx16 s[36:51], s[0:1], 0x40
	v_writelane_b32 v252, s3, 50
	s_mov_b32 s2, s22
	v_writelane_b32 v252, s2, 51
	s_nop 1
	v_writelane_b32 v252, s3, 52
	s_lshl_b64 s[2:3], s[22:23], 11
	v_writelane_b32 v252, s2, 53
	s_nop 1
	v_writelane_b32 v252, s3, 54
	s_mov_b32 s2, s24
	v_writelane_b32 v252, s2, 55
	s_nop 1
	v_writelane_b32 v252, s3, 56
	s_lshl_b64 s[2:3], s[28:29], 6
	v_writelane_b32 v252, s2, 57
	s_nop 1
	v_writelane_b32 v252, s3, 58
	s_lshl_b64 s[2:3], s[28:29], 12
	v_writelane_b32 v252, s2, 59
	s_nop 1
	v_writelane_b32 v252, s3, 60
	s_mov_b32 s2, s28
	v_writelane_b32 v252, s2, 61
	s_nop 1
	v_writelane_b32 v252, s3, 62
	s_lshl_b64 s[2:3], s[28:29], 11
	v_writelane_b32 v252, s2, 63
	s_nop 1
	v_writelane_b32 v253, s3, 0
	s_add_u32 s2, s12, 0x3b30080
	v_writelane_b32 v253, s2, 1
	s_addc_u32 s2, s13, 0
	v_writelane_b32 v253, s2, 2
	s_add_i32 s2, 0, 0xffffc720
	v_writelane_b32 v253, s2, 3
	s_add_i32 s2, 0, 0x21400
	v_writelane_b32 v253, s2, 4
	s_add_i32 s2, 0, 0x10800
	v_writelane_b32 v253, s2, 5
	s_add_i32 s2, 0, 0x20c00
	v_writelane_b32 v253, s2, 6
	s_add_i32 s2, 0, 0x18800
	v_writelane_b32 v253, s2, 7
	s_add_i32 s2, 0, 0x25fc0
	v_writelane_b32 v253, s2, 8
	s_add_i32 s2, 0, 0x25fc4
	v_writelane_b32 v253, s2, 9
	s_waitcnt lgkmcnt(0)
	v_writelane_b32 v253, s36, 10
	s_nop 1
	v_writelane_b32 v253, s37, 11
	v_writelane_b32 v253, s38, 12
	v_writelane_b32 v253, s39, 13
	v_writelane_b32 v253, s40, 14
	v_writelane_b32 v253, s41, 15
	v_writelane_b32 v253, s42, 16
	v_writelane_b32 v253, s43, 17
	v_writelane_b32 v253, s44, 18
	v_writelane_b32 v253, s45, 19
	v_writelane_b32 v253, s46, 20
	v_writelane_b32 v253, s47, 21
	v_writelane_b32 v253, s48, 22
	v_writelane_b32 v253, s49, 23
	v_writelane_b32 v253, s50, 24
	v_writelane_b32 v253, s51, 25
	s_load_dwordx16 s[36:51], s[0:1], 0x80
	s_waitcnt lgkmcnt(0)
	v_writelane_b32 v253, s36, 26
	s_nop 1
	v_writelane_b32 v253, s37, 27
	v_writelane_b32 v253, s38, 28
	v_writelane_b32 v253, s39, 29
	v_writelane_b32 v253, s40, 30
	v_writelane_b32 v253, s41, 31
	v_writelane_b32 v253, s42, 32
	v_writelane_b32 v253, s43, 33
	v_writelane_b32 v253, s44, 34
	v_writelane_b32 v253, s45, 35
	v_writelane_b32 v253, s46, 36
	v_writelane_b32 v253, s47, 37
	v_writelane_b32 v253, s48, 38
	v_writelane_b32 v253, s49, 39
	v_writelane_b32 v253, s50, 40
	v_writelane_b32 v253, s51, 41
	v_writelane_b32 v253, s26, 42
	v_writelane_b32 v253, s84, 43
	v_writelane_b32 v253, s85, 44
	v_writelane_b32 v253, s86, 45
	v_writelane_b32 v253, s87, 46
	s_mov_b64 s[50:51], s[4:5]
	v_writelane_b32 v253, s96, 47
	v_writelane_b32 v253, s50, 48
	s_nop 1
	v_writelane_b32 v253, s51, 49
	s_mov_b32 s98, 0
	s_nop 1
	v_writelane_b32 v255, s98, 62
	s_branch .LBB0_11

.LBB0_76:
	s_nop 0
	v_lshlrev_b32_e32 v86, 16, v85
	v_and_b32_e32 v87, 0xffff0000, v85
	s_waitcnt lgkmcnt(0)
	v_pk_fma_f32 v[16:17], v[14:15], v[16:17], v[86:87]
	s_mov_b64 s[30:31], exec
	v_cvt_pk_bf16_f32 v14, v16, v16
	v_bfe_u32 v15, v17, 16, 1
	v_lshrrev_b32_e32 v14, 16, v14
	v_add3_u32 v15, v17, v15, s94
	v_and_or_b32 v14, v15, s33, v14

.LBB0_464:
	v_ashrrev_i32_e32 v151, 31, v150
	v_lshlrev_b64 v[6:7], 9, v[150:151]
	v_lshl_add_u64 v[38:39], v[148:149], 0, v[6:7]
	global_load_dwordx4 v[40:43], v[38:39], off
	global_load_dwordx4 v[44:47], v[38:39], off offset:1024
	global_load_dwordx4 v[48:51], v[38:39], off offset:2048
	global_load_dwordx4 v[52:55], v[38:39], off offset:3072
	v_add_co_u32_e32 v6, vcc, s12, v38
	s_movk_i32 s4, 0x3000
	s_nop 0
	v_addc_co_u32_e32 v7, vcc, 0, v39, vcc
	v_add_co_u32_e32 v8, vcc, s68, v38
	v_add_u32_e32 v151, s22, v243
	s_nop 0
	v_addc_co_u32_e32 v9, vcc, 0, v39, vcc
	v_add_co_u32_e32 v14, vcc, s4, v38
	global_load_dwordx4 v[56:59], v[8:9], off offset:-4096
	global_load_dwordx4 v[60:63], v[6:7], off offset:1024
	global_load_dwordx4 v[64:67], v[6:7], off offset:2048
	global_load_dwordx4 v[68:71], v[6:7], off offset:3072
	global_load_dwordx4 v[26:29], v[8:9], off
	global_load_dwordx4 v[18:21], v[8:9], off offset:1024
	global_load_dwordx4 v[10:13], v[8:9], off offset:2048
	s_nop 0
	global_load_dwordx4 v[6:9], v[8:9], off offset:3072
	v_addc_co_u32_e32 v15, vcc, 0, v39, vcc
	v_add_co_u32_e32 v88, vcc, s69, v38
	s_movk_i32 s4, 0x5000
	s_nop 0
	v_addc_co_u32_e32 v89, vcc, 0, v39, vcc
	global_load_dwordx4 v[34:37], v[88:89], off offset:-4096
	global_load_dwordx4 v[30:33], v[14:15], off offset:1024
	global_load_dwordx4 v[22:25], v[14:15], off offset:2048
	s_nop 0
	global_load_dwordx4 v[14:17], v[14:15], off offset:3072
	ds_read_b128 v[158:161], v151 offset:14560
	ds_read_b128 v[162:165], v151 offset:31200
	ds_read_b128 v[166:169], v151 offset:47840
	ds_read_b128 v[170:173], v151 offset:64480
	ds_read_b128 v[174:177], v151 offset:12480
	v_ashrrev_i32_e32 v157, 31, v156
	v_add_u32_e32 v150, 64, v150
	v_add_u32_e32 v243, 32, v243
	s_waitcnt vmcnt(15)
	s_waitcnt lgkmcnt(4)
	v_mfma_f32_16x16x32_bf16 v[72:75], v[40:43], v[158:161], 0
	ds_read_b128 v[178:181], v151 offset:29120
	s_waitcnt lgkmcnt(4)
	v_mfma_f32_16x16x32_bf16 v[76:79], v[40:43], v[162:165], 0
	ds_read_b128 v[182:185], v151 offset:45760
	s_waitcnt lgkmcnt(4)
	v_mfma_f32_16x16x32_bf16 v[80:83], v[40:43], v[166:169], 0
	ds_read_b128 v[186:189], v151 offset:62400
	s_waitcnt lgkmcnt(4)
	v_mfma_f32_16x16x32_bf16 v[40:43], v[40:43], v[170:173], 0
	ds_read_b128 v[158:161], v151 offset:10400
	s_waitcnt vmcnt(14)
	s_waitcnt lgkmcnt(4)
	v_mfma_f32_16x16x32_bf16 v[72:75], v[44:47], v[174:177], v[72:75]
	ds_read_b128 v[162:165], v151 offset:27040
	s_waitcnt lgkmcnt(4)
	v_mfma_f32_16x16x32_bf16 v[76:79], v[44:47], v[178:181], v[76:79]
	ds_read_b128 v[166:169], v151 offset:43680
	s_waitcnt lgkmcnt(4)
	v_mfma_f32_16x16x32_bf16 v[80:83], v[44:47], v[182:185], v[80:83]
	ds_read_b128 v[170:173], v151 offset:60320
	s_waitcnt lgkmcnt(4)
	v_mfma_f32_16x16x32_bf16 v[40:43], v[44:47], v[186:189], v[40:43]
	ds_read_b128 v[174:177], v151 offset:8320
	s_waitcnt vmcnt(13)
	s_waitcnt lgkmcnt(4)
	v_mfma_f32_16x16x32_bf16 v[44:47], v[48:51], v[158:161], v[72:75]
	ds_read_b128 v[178:181], v151 offset:24960
	s_waitcnt lgkmcnt(4)
	v_mfma_f32_16x16x32_bf16 v[72:75], v[48:51], v[162:165], v[76:79]
	ds_read_b128 v[182:185], v151 offset:41600
	s_waitcnt lgkmcnt(4)
	v_mfma_f32_16x16x32_bf16 v[76:79], v[48:51], v[166:169], v[80:83]
	ds_read_b128 v[186:189], v151 offset:58240
	s_waitcnt lgkmcnt(4)
	v_mfma_f32_16x16x32_bf16 v[40:43], v[48:51], v[170:173], v[40:43]
	ds_read_b128 v[158:161], v151 offset:6240
	s_waitcnt vmcnt(12)
	s_waitcnt lgkmcnt(4)
	v_mfma_f32_16x16x32_bf16 v[44:47], v[52:55], v[174:177], v[44:47]
	ds_read_b128 v[162:165], v151 offset:22880
	s_waitcnt lgkmcnt(4)
	v_mfma_f32_16x16x32_bf16 v[48:51], v[52:55], v[178:181], v[72:75]
	ds_read_b128 v[166:169], v151 offset:39520
	s_waitcnt lgkmcnt(4)
	v_mfma_f32_16x16x32_bf16 v[72:75], v[52:55], v[182:185], v[76:79]
	ds_read_b128 v[170:173], v151 offset:56160
	s_waitcnt lgkmcnt(4)
	v_mfma_f32_16x16x32_bf16 v[40:43], v[52:55], v[186:189], v[40:43]
	ds_read_b128 v[174:177], v151 offset:4160
	s_waitcnt vmcnt(11)
	s_waitcnt lgkmcnt(4)
	v_mfma_f32_16x16x32_bf16 v[44:47], v[56:59], v[158:161], v[44:47]
	ds_read_b128 v[178:181], v151 offset:20800
	s_waitcnt lgkmcnt(4)
	v_mfma_f32_16x16x32_bf16 v[48:51], v[56:59], v[162:165], v[48:51]
	ds_read_b128 v[182:185], v151 offset:37440
	s_waitcnt lgkmcnt(4)
	v_mfma_f32_16x16x32_bf16 v[52:55], v[56:59], v[166:169], v[72:75]
	ds_read_b128 v[186:189], v151 offset:54080
	s_waitcnt lgkmcnt(4)
	v_mfma_f32_16x16x32_bf16 v[40:43], v[56:59], v[170:173], v[40:43]
	ds_read_b128 v[158:161], v151 offset:2080
	s_waitcnt vmcnt(10)
	s_waitcnt lgkmcnt(4)
	v_mfma_f32_16x16x32_bf16 v[44:47], v[60:63], v[174:177], v[44:47]
	ds_read_b128 v[162:165], v151 offset:18720
	s_waitcnt lgkmcnt(4)
	v_mfma_f32_16x16x32_bf16 v[48:51], v[60:63], v[178:181], v[48:51]
	ds_read_b128 v[166:169], v151 offset:35360
	s_waitcnt lgkmcnt(4)
	v_mfma_f32_16x16x32_bf16 v[52:55], v[60:63], v[182:185], v[52:55]
	ds_read_b128 v[170:173], v151 offset:52000
	s_waitcnt lgkmcnt(4)
	v_mfma_f32_16x16x32_bf16 v[40:43], v[60:63], v[186:189], v[40:43]
	ds_read_b128 v[174:177], v151
	s_waitcnt vmcnt(9)
	s_waitcnt lgkmcnt(4)
	v_mfma_f32_16x16x32_bf16 v[44:47], v[64:67], v[158:161], v[44:47]
	ds_read_b128 v[178:181], v151 offset:16640
	s_waitcnt lgkmcnt(4)
	v_mfma_f32_16x16x32_bf16 v[48:51], v[64:67], v[162:165], v[48:51]
	ds_read_b128 v[182:185], v151 offset:33280
	s_waitcnt lgkmcnt(4)
	v_mfma_f32_16x16x32_bf16 v[58:61], v[64:67], v[166:169], v[52:55]
	ds_read_b128 v[186:189], v151 offset:49920
	s_waitcnt lgkmcnt(4)
	v_mfma_f32_16x16x32_bf16 v[40:43], v[64:67], v[170:173], v[40:43]
	ds_read_b128 v[158:161], v151 offset:14560
	s_waitcnt vmcnt(8)
	s_waitcnt lgkmcnt(4)
	v_mfma_f32_16x16x32_bf16 v[54:57], v[68:71], v[174:177], v[44:47]
	ds_read_b128 v[162:165], v151 offset:31200
	v_add_co_u32_e32 v52, vcc, s4, v38
	s_waitcnt lgkmcnt(4)
	v_mfma_f32_16x16x32_bf16 v[44:47], v[68:71], v[178:181], v[48:51]
	ds_read_b128 v[166:169], v151 offset:47840
	v_addc_co_u32_e32 v53, vcc, 0, v39, vcc
	s_waitcnt lgkmcnt(4)
	v_mfma_f32_16x16x32_bf16 v[48:51], v[68:71], v[182:185], v[58:61]
	ds_read_b128 v[170:173], v151 offset:12480
	v_add_co_u32_e32 v102, vcc, s70, v38
	s_nop 1
	v_addc_co_u32_e32 v103, vcc, 0, v39, vcc
	s_waitcnt lgkmcnt(4)
	v_mfma_f32_16x16x32_bf16 v[40:43], v[68:71], v[186:189], v[40:43]
	ds_read_b128 v[174:177], v151 offset:29120
	global_load_dwordx4 v[70:73], v[88:89], off
	global_load_dwordx4 v[66:69], v[88:89], off offset:1024
	global_load_dwordx4 v[62:65], v[88:89], off offset:2048
	global_load_dwordx4 v[58:61], v[88:89], off offset:3072
	global_load_dwordx4 v[86:89], v[102:103], off offset:-4096
	global_load_dwordx4 v[82:85], v[52:53], off offset:1024
	global_load_dwordx4 v[78:81], v[52:53], off offset:2048
	global_load_dwordx4 v[74:77], v[52:53], off offset:3072
	s_waitcnt vmcnt(15)
	s_waitcnt lgkmcnt(4)
	v_mfma_f32_16x16x32_bf16 v[44:47], v[26:29], v[158:161], v[44:47]
	ds_read_b128 v[178:181], v151 offset:45760
	s_movk_i32 s4, 0x7000
	s_waitcnt lgkmcnt(4)
	v_mfma_f32_16x16x32_bf16 v[48:51], v[26:29], v[162:165], v[48:51]
	ds_read_b128 v[182:185], v151 offset:10400
	s_waitcnt lgkmcnt(4)
	v_mfma_f32_16x16x32_bf16 v[26:29], v[26:29], v[166:169], v[40:43]
	ds_read_b128 v[186:189], v151 offset:27040
	s_waitcnt vmcnt(14)
	s_waitcnt lgkmcnt(4)
	v_mfma_f32_16x16x32_bf16 v[40:43], v[18:21], v[170:173], v[44:47]
	ds_read_b128 v[158:161], v151 offset:43680
	s_waitcnt lgkmcnt(4)
	v_mfma_f32_16x16x32_bf16 v[44:47], v[18:21], v[174:177], v[48:51]
	ds_read_b128 v[162:165], v151 offset:8320
	s_waitcnt lgkmcnt(4)
	v_mfma_f32_16x16x32_bf16 v[18:21], v[18:21], v[178:181], v[26:29]
	ds_read_b128 v[166:169], v151 offset:24960
	s_waitcnt vmcnt(13)
	s_waitcnt lgkmcnt(4)
	v_mfma_f32_16x16x32_bf16 v[26:29], v[10:13], v[182:185], v[40:43]
	ds_read_b128 v[170:173], v151 offset:41600
	s_waitcnt lgkmcnt(4)
	v_mfma_f32_16x16x32_bf16 v[40:43], v[10:13], v[186:189], v[44:47]
	ds_read_b128 v[174:177], v151 offset:6240
	s_waitcnt lgkmcnt(4)
	v_mfma_f32_16x16x32_bf16 v[10:13], v[10:13], v[158:161], v[18:21]
	ds_read_b128 v[178:181], v151 offset:22880
	s_waitcnt vmcnt(12)
	s_waitcnt lgkmcnt(4)
	v_mfma_f32_16x16x32_bf16 v[18:21], v[6:9], v[162:165], v[26:29]
	ds_read_b128 v[182:185], v151 offset:39520
	s_waitcnt lgkmcnt(4)
	v_mfma_f32_16x16x32_bf16 v[26:29], v[6:9], v[166:169], v[40:43]
	ds_read_b128 v[186:189], v151 offset:4160
	s_waitcnt lgkmcnt(4)
	v_mfma_f32_16x16x32_bf16 v[6:9], v[6:9], v[170:173], v[10:13]
	ds_read_b128 v[158:161], v151 offset:20800
	s_waitcnt vmcnt(11)
	s_waitcnt lgkmcnt(4)
	v_mfma_f32_16x16x32_bf16 v[10:13], v[34:37], v[174:177], v[18:21]
	ds_read_b128 v[162:165], v151 offset:37440
	s_waitcnt lgkmcnt(4)
	v_mfma_f32_16x16x32_bf16 v[18:21], v[34:37], v[178:181], v[26:29]
	ds_read_b128 v[166:169], v151 offset:2080
	s_waitcnt lgkmcnt(4)
	v_mfma_f32_16x16x32_bf16 v[6:9], v[34:37], v[182:185], v[6:9]
	ds_read_b128 v[170:173], v151 offset:18720
	s_waitcnt vmcnt(10)
	s_waitcnt lgkmcnt(4)
	v_mfma_f32_16x16x32_bf16 v[10:13], v[30:33], v[186:189], v[10:13]
	ds_read_b128 v[174:177], v151 offset:35360
	s_waitcnt lgkmcnt(4)
	v_mfma_f32_16x16x32_bf16 v[18:21], v[30:33], v[158:161], v[18:21]
	ds_read_b128 v[178:181], v151
	s_waitcnt lgkmcnt(4)
	v_mfma_f32_16x16x32_bf16 v[6:9], v[30:33], v[162:165], v[6:9]
	ds_read_b128 v[182:185], v151 offset:16640
	s_waitcnt vmcnt(9)
	s_waitcnt lgkmcnt(4)
	v_mfma_f32_16x16x32_bf16 v[10:13], v[22:25], v[166:169], v[10:13]
	ds_read_b128 v[186:189], v151 offset:33280
	s_waitcnt lgkmcnt(4)
	v_mfma_f32_16x16x32_bf16 v[18:21], v[22:25], v[170:173], v[18:21]
	s_waitcnt lgkmcnt(3)
	v_mfma_f32_16x16x32_bf16 v[6:9], v[22:25], v[174:177], v[6:9]
	v_lshl_add_u64 v[26:27], v[156:157], 3, s[0:1]
	v_add_u32_e32 v156, 64, v156
	s_waitcnt vmcnt(8)
	s_waitcnt lgkmcnt(2)
	v_mfma_f32_16x16x32_bf16 v[50:53], v[14:17], v[178:181], v[10:13]
	s_waitcnt lgkmcnt(1)
	v_mfma_f32_16x16x32_bf16 v[106:109], v[14:17], v[182:185], v[18:21]
	global_load_dwordx4 v[90:93], v[102:103], off
	global_load_dwordx4 v[94:97], v[102:103], off offset:1024
	global_load_dwordx4 v[98:101], v[102:103], off offset:2048
	global_load_dwordx4 v[102:105], v[102:103], off offset:3072
	s_waitcnt lgkmcnt(0)
	v_mfma_f32_16x16x32_bf16 v[110:113], v[14:17], v[186:189], v[6:9]
	s_nop 2
	v_add_co_u32_e32 v6, vcc, s4, v38
	v_add_u32_e32 v8, s23, v239
	s_nop 0
	v_addc_co_u32_e32 v7, vcc, 0, v39, vcc
	global_load_dwordx4 v[118:121], v[6:7], off
	global_load_dwordx4 v[122:125], v[6:7], off offset:1024
	global_load_dwordx4 v[126:129], v[6:7], off offset:2048
	global_load_dwordx4 v[130:133], v[6:7], off offset:3072
	global_load_dwordx4 v[46:49], v[152:153], off offset:-128
	v_add_u32_e32 v6, s23, v240
	v_ashrrev_i32_e32 v7, 31, v6
	v_lshl_add_u64 v[10:11], v[6:7], 3, s[96:97]
	v_ashrrev_i32_e32 v9, 31, v8
	global_load_dwordx2 v[218:219], v[10:11], off offset:8
	v_lshl_add_u64 v[10:11], v[8:9], 3, s[96:97]
	global_load_dwordx2 v[208:209], v[10:11], off offset:128
	v_add_u32_e32 v10, 17, v8
	v_add_u32_e32 v12, 17, v6
	v_ashrrev_i32_e32 v13, 31, v12
	v_ashrrev_i32_e32 v11, 31, v10
	v_lshl_add_u64 v[12:13], v[12:13], 3, s[96:97]
	v_lshl_add_u64 v[10:11], v[10:11], 3, s[96:97]
	global_load_dwordx4 v[114:117], v[26:27], off offset:16
	global_load_dwordx4 v[134:137], v[26:27], off
	global_load_dwordx2 v[214:215], v[12:13], off offset:8
	global_load_dwordx2 v[206:207], v[10:11], off offset:128
	v_add_u32_e32 v10, 34, v8
	v_add_u32_e32 v12, 34, v6
	v_ashrrev_i32_e32 v13, 31, v12
	v_ashrrev_i32_e32 v11, 31, v10
	v_lshl_add_u64 v[12:13], v[12:13], 3, s[96:97]
	v_lshl_add_u64 v[10:11], v[10:11], 3, s[96:97]
	global_load_dwordx2 v[220:221], v[12:13], off offset:8
	global_load_dwordx2 v[212:213], v[10:11], off offset:128
	v_add_u32_e32 v10, 51, v8
	v_add_u32_e32 v12, 51, v6
	v_ashrrev_i32_e32 v13, 31, v12
	v_ashrrev_i32_e32 v11, 31, v10
	v_lshl_add_u64 v[12:13], v[12:13], 3, s[96:97]
	v_lshl_add_u64 v[10:11], v[10:11], 3, s[96:97]
	global_load_dwordx2 v[216:217], v[12:13], off offset:8
	global_load_dwordx2 v[210:211], v[10:11], off offset:128
	global_load_dwordx4 v[34:37], v[152:153], off offset:-64
	v_add_u32_e32 v10, 0x110, v8
	v_add_u32_e32 v12, 0x110, v6
	v_ashrrev_i32_e32 v13, 31, v12
	v_ashrrev_i32_e32 v11, 31, v10
	v_lshl_add_u64 v[12:13], v[12:13], 3, s[96:97]
	v_lshl_add_u64 v[10:11], v[10:11], 3, s[96:97]
	global_load_dwordx2 v[202:203], v[12:13], off offset:8
	global_load_dwordx2 v[192:193], v[10:11], off offset:128
	global_load_dwordx4 v[38:41], v[26:27], off offset:144
	global_load_dwordx4 v[42:45], v[26:27], off offset:128
	v_add_u32_e32 v10, 0x121, v8
	v_add_u32_e32 v12, 0x121, v6
	v_ashrrev_i32_e32 v13, 31, v12
	v_ashrrev_i32_e32 v11, 31, v10
	v_lshl_add_u64 v[12:13], v[12:13], 3, s[96:97]
	v_lshl_add_u64 v[10:11], v[10:11], 3, s[96:97]
	global_load_dwordx2 v[198:199], v[12:13], off offset:8
	global_load_dwordx2 v[190:191], v[10:11], off offset:128
	v_add_u32_e32 v10, 0x132, v8
	v_add_u32_e32 v12, 0x132, v6
	v_ashrrev_i32_e32 v13, 31, v12
	v_ashrrev_i32_e32 v11, 31, v10
	v_lshl_add_u64 v[12:13], v[12:13], 3, s[96:97]
	v_lshl_add_u64 v[10:11], v[10:11], 3, s[96:97]
	global_load_dwordx2 v[204:205], v[12:13], off offset:8
	global_load_dwordx2 v[196:197], v[10:11], off offset:128
	v_add_u32_e32 v10, 0x143, v8
	v_add_u32_e32 v12, 0x143, v6
	v_ashrrev_i32_e32 v13, 31, v12
	v_ashrrev_i32_e32 v11, 31, v10
	v_lshl_add_u64 v[12:13], v[12:13], 3, s[96:97]
	v_lshl_add_u64 v[10:11], v[10:11], 3, s[96:97]
	global_load_dwordx2 v[200:201], v[12:13], off offset:8
	global_load_dwordx2 v[194:195], v[10:11], off offset:128
	global_load_dwordx4 v[14:17], v[152:153], off
	v_add_u32_e32 v10, 0x220, v8
	v_add_u32_e32 v12, 0x220, v6
	v_ashrrev_i32_e32 v13, 31, v12
	v_ashrrev_i32_e32 v11, 31, v10
	v_lshl_add_u64 v[12:13], v[12:13], 3, s[96:97]
	v_lshl_add_u64 v[10:11], v[10:11], 3, s[96:97]
	global_load_dwordx2 v[184:185], v[12:13], off offset:8
	global_load_dwordx2 v[178:179], v[10:11], off offset:128
	global_load_dwordx4 v[22:25], v[26:27], off offset:272
	global_load_dwordx4 v[30:33], v[26:27], off offset:256
	v_add_u32_e32 v10, 0x231, v8
	v_add_u32_e32 v12, 0x231, v6
	v_ashrrev_i32_e32 v13, 31, v12
	v_ashrrev_i32_e32 v11, 31, v10
	v_lshl_add_u64 v[12:13], v[12:13], 3, s[96:97]
	v_lshl_add_u64 v[10:11], v[10:11], 3, s[96:97]
	global_load_dwordx2 v[182:183], v[12:13], off offset:8
	global_load_dwordx2 v[172:173], v[10:11], off offset:128
	v_add_u32_e32 v10, 0x242, v8
	v_add_u32_e32 v12, 0x242, v6
	v_ashrrev_i32_e32 v13, 31, v12
	v_ashrrev_i32_e32 v11, 31, v10
	v_lshl_add_u64 v[12:13], v[12:13], 3, s[96:97]
	v_lshl_add_u64 v[10:11], v[10:11], 3, s[96:97]
	global_load_dwordx2 v[186:187], v[12:13], off offset:8
	global_load_dwordx2 v[180:181], v[10:11], off offset:128
	v_add_u32_e32 v10, 0x253, v8
	v_add_u32_e32 v12, 0x253, v6
	v_add_u32_e32 v18, 0x330, v8
	v_add_u32_e32 v20, 0x330, v6
	v_add_u32_e32 v140, 0x341, v8
	v_add_u32_e32 v142, 0x341, v6
	v_ashrrev_i32_e32 v13, 31, v12
	v_ashrrev_i32_e32 v11, 31, v10
	v_ashrrev_i32_e32 v21, 31, v20
	v_ashrrev_i32_e32 v19, 31, v18
	v_ashrrev_i32_e32 v143, 31, v142
	v_ashrrev_i32_e32 v141, 31, v140
	v_lshl_add_u64 v[12:13], v[12:13], 3, s[96:97]
	v_lshl_add_u64 v[10:11], v[10:11], 3, s[96:97]
	v_lshl_add_u64 v[20:21], v[20:21], 3, s[96:97]
	v_lshl_add_u64 v[18:19], v[18:19], 3, s[96:97]
	v_lshl_add_u64 v[142:143], v[142:143], 3, s[96:97]
	v_lshl_add_u64 v[140:141], v[140:141], 3, s[96:97]
	global_load_dwordx2 v[176:177], v[12:13], off offset:8
	global_load_dwordx2 v[170:171], v[10:11], off offset:128
	s_nop 0
	global_load_dwordx4 v[10:13], v[152:153], off offset:64
	global_load_dwordx2 v[162:163], v[20:21], off offset:8
	global_load_dwordx2 v[160:161], v[18:19], off offset:128
	s_nop 0
	global_load_dwordx4 v[18:21], v[26:27], off offset:400
	s_nop 0
	global_load_dwordx4 v[26:29], v[26:27], off offset:384
	s_addk_i32 s23, 0x440
	global_load_dwordx2 v[164:165], v[142:143], off offset:8
	global_load_dwordx2 v[158:159], v[140:141], off offset:128
	v_add_u32_e32 v142, 0x352, v6
	v_add_u32_e32 v6, 0x363, v6
	v_ashrrev_i32_e32 v7, 31, v6
	v_lshl_add_u64 v[6:7], v[6:7], 3, s[96:97]
	global_load_dwordx2 v[174:175], v[6:7], off offset:8
	v_add_u32_e32 v140, 0x352, v8
	v_add_u32_e32 v8, 0x363, v8
	v_ashrrev_i32_e32 v143, 31, v142
	v_ashrrev_i32_e32 v141, 31, v140
	v_ashrrev_i32_e32 v9, 31, v8
	v_lshl_add_u64 v[142:143], v[142:143], 3, s[96:97]
	v_lshl_add_u64 v[140:141], v[140:141], 3, s[96:97]
	v_lshl_add_u64 v[6:7], v[8:9], 3, s[96:97]
	global_load_dwordx2 v[168:169], v[142:143], off offset:8
	global_load_dwordx2 v[166:167], v[140:141], off offset:128
	global_load_dwordx2 v[188:189], v[6:7], off offset:128
	s_nop 0
	global_load_dwordx4 v[6:9], v[154:155], off
	ds_read_b128 v[244:247], v151 offset:14560
	ds_read_b128 v[140:143], v151 offset:31200
	s_waitcnt vmcnt(60) lgkmcnt(1)
	v_mfma_f32_16x16x32_bf16 v[106:109], v[70:73], v[244:247], v[106:109]
	v_lshl_add_u64 v[152:153], v[152:153], 0, s[14:15]
	v_lshl_add_u64 v[154:155], v[154:155], 0, 64
	s_cmpk_eq_i32 s23, 0x1100
	s_waitcnt lgkmcnt(0)
	v_mfma_f32_16x16x32_bf16 v[70:73], v[70:73], v[140:143], v[110:113]
	ds_read_b128 v[140:143], v151 offset:29120
	s_nop 1
	ds_read_b128 v[110:113], v151 offset:12480
	s_waitcnt vmcnt(59) lgkmcnt(0)
	v_mfma_f32_16x16x32_bf16 v[106:109], v[66:69], v[110:113], v[106:109]
	v_mfma_f32_16x16x32_bf16 v[66:69], v[66:69], v[140:143], v[70:73]
	ds_read_b128 v[140:143], v151 offset:27040
	s_nop 1
	ds_read_b128 v[70:73], v151 offset:10400
	s_waitcnt vmcnt(58) lgkmcnt(0)
	v_mfma_f32_16x16x32_bf16 v[106:109], v[62:65], v[70:73], v[106:109]
	v_mfma_f32_16x16x32_bf16 v[62:65], v[62:65], v[140:143], v[66:69]
	ds_read_b128 v[140:143], v151 offset:24960
	s_nop 1
	ds_read_b128 v[66:69], v151 offset:8320
	s_waitcnt vmcnt(57) lgkmcnt(0)
	v_mfma_f32_16x16x32_bf16 v[106:109], v[58:61], v[66:69], v[106:109]
	v_mfma_f32_16x16x32_bf16 v[58:61], v[58:61], v[140:143], v[62:65]
	ds_read_b128 v[140:143], v151 offset:6240
	s_waitcnt vmcnt(56) lgkmcnt(0)
	v_mfma_f32_16x16x32_bf16 v[62:65], v[86:89], v[140:143], v[106:109]
	s_nop 3
	ds_read_b128 v[106:109], v151 offset:22880
	s_waitcnt lgkmcnt(0)
	v_mfma_f32_16x16x32_bf16 v[58:61], v[86:89], v[106:109], v[58:61]
	ds_read_b128 v[86:89], v151 offset:4160
	ds_read_b128 v[106:109], v151 offset:20800
	s_waitcnt vmcnt(55) lgkmcnt(1)
	v_mfma_f32_16x16x32_bf16 v[62:65], v[82:85], v[86:89], v[62:65]
	s_waitcnt lgkmcnt(0)
	v_mfma_f32_16x16x32_bf16 v[58:61], v[82:85], v[106:109], v[58:61]
	ds_read_b128 v[82:85], v151 offset:2080
	ds_read_b128 v[106:109], v151 offset:18720
	s_waitcnt vmcnt(54) lgkmcnt(1)
	v_mfma_f32_16x16x32_bf16 v[62:65], v[78:81], v[82:85], v[62:65]
	s_waitcnt lgkmcnt(0)
	v_mfma_f32_16x16x32_bf16 v[58:61], v[78:81], v[106:109], v[58:61]
	ds_read_b128 v[78:81], v151
	ds_read_b128 v[106:109], v151 offset:16640
	s_waitcnt vmcnt(53) lgkmcnt(0)
	v_mfma_f32_16x16x32_bf16 v[58:61], v[74:77], v[106:109], v[58:61]
	s_waitcnt vmcnt(52)
	v_mfma_f32_16x16x32_bf16 v[58:61], v[90:93], v[244:247], v[58:61]
	s_waitcnt vmcnt(51)
	v_mfma_f32_16x16x32_bf16 v[58:61], v[94:97], v[110:113], v[58:61]
	s_waitcnt vmcnt(50)
	v_mfma_f32_16x16x32_bf16 v[58:61], v[98:101], v[70:73], v[58:61]
	s_waitcnt vmcnt(40)
	v_mov_b32_e32 v72, v134
	v_mov_b32_e32 v73, v136
	v_mov_b32_e32 v70, v114
	v_mfma_f32_16x16x32_bf16 v[58:61], v[102:105], v[66:69], v[58:61]
	v_mov_b32_e32 v71, v116
	v_mov_b32_e32 v136, v135
	v_mov_b32_e32 v116, v115
	v_mfma_f32_16x16x32_bf16 v[58:61], v[118:121], v[140:143], v[58:61]
	v_mfma_f32_16x16x32_bf16 v[58:61], v[122:125], v[86:89], v[58:61]
	v_mfma_f32_16x16x32_bf16 v[58:61], v[126:129], v[82:85], v[58:61]
	v_mfma_f32_16x16x32_bf16 v[62:65], v[74:77], v[78:81], v[62:65]
	s_waitcnt vmcnt(39)
	v_mov_b32_e32 v75, v214
	v_mov_b32_e32 v214, v219
	s_waitcnt vmcnt(35)
	v_mov_b32_e32 v77, v216
	v_mov_b32_e32 v216, v221
	v_mfma_f32_16x16x32_bf16 v[66:69], v[130:133], v[78:81], v[58:61]
	v_mov_b32_e32 v74, v218
	v_mov_b32_e32 v76, v220
	v_pk_mul_f32 v[80:81], v[216:217], v[70:71]
	v_pk_mul_f32 v[60:61], v[214:215], v[72:73]
	v_pk_mul_f32 v[58:59], v[214:215], v[136:137]
	v_pk_fma_f32 v[60:61], v[74:75], v[136:137], v[60:61]
	v_pk_mul_f32 v[78:79], v[216:217], v[116:117]
	v_pk_fma_f32 v[80:81], v[76:77], v[116:117], v[80:81]
	v_pk_fma_f32 v[58:59], v[74:75], v[72:73], v[58:59] neg_lo:[0,0,1] neg_hi:[0,0,1]
	v_pk_fma_f32 v[78:79], v[76:77], v[70:71], v[78:79] neg_lo:[0,0,1] neg_hi:[0,0,1]
	v_cvt_pk_bf16_f32 v59, v59, v61
	v_cvt_pk_bf16_f32 v61, v79, v81
	v_cvt_pk_bf16_f32 v58, v58, v60
	v_cvt_pk_bf16_f32 v60, v78, v80
	v_mov_b32_e32 v79, v206
	v_mov_b32_e32 v206, v209
	v_mfma_f32_16x16x32_bf16 v[54:57], v[46:49], v[58:61], v[54:57]
	v_mov_b32_e32 v78, v208
	v_pk_mul_f32 v[58:59], v[214:215], v[206:207]
	v_mov_b32_e32 v82, v212
	s_waitcnt vmcnt(34)
	v_mov_b32_e32 v83, v210
	v_mov_b32_e32 v210, v213
	v_pk_fma_f32 v[80:81], v[74:75], v[78:79], v[58:59] neg_lo:[0,0,1] neg_hi:[0,0,1]
	v_pk_mul_f32 v[58:59], v[214:215], v[78:79]
	v_pk_mul_f32 v[84:85], v[216:217], v[210:211]
	v_pk_mul_f32 v[86:87], v[216:217], v[82:83]
	v_pk_fma_f32 v[74:75], v[74:75], v[206:207], v[58:59]
	v_pk_fma_f32 v[84:85], v[76:77], v[82:83], v[84:85] neg_lo:[0,0,1] neg_hi:[0,0,1]
	v_pk_fma_f32 v[76:77], v[76:77], v[210:211], v[86:87]
	v_pk_mul_f32 v[60:61], v[72:73], v[74:75]
	v_pk_mul_f32 v[88:89], v[70:71], v[76:77]
	v_pk_mul_f32 v[58:59], v[136:137], v[74:75]
	v_pk_fma_f32 v[60:61], v[136:137], v[80:81], v[60:61]
	v_pk_mul_f32 v[86:87], v[116:117], v[76:77]
	v_pk_fma_f32 v[88:89], v[116:117], v[84:85], v[88:89]
	v_pk_fma_f32 v[58:59], v[72:73], v[80:81], v[58:59] neg_lo:[0,0,1] neg_hi:[0,0,1]
	v_pk_fma_f32 v[86:87], v[70:71], v[84:85], v[86:87] neg_lo:[0,0,1] neg_hi:[0,0,1]
	v_cvt_pk_bf16_f32 v59, v59, v61
	v_cvt_pk_bf16_f32 v61, v87, v89
	v_cvt_pk_bf16_f32 v58, v58, v60
	v_cvt_pk_bf16_f32 v60, v86, v88
	s_nop 1
	v_mfma_f32_16x16x32_bf16 v[58:61], v[46:49], v[58:61], v[50:53]
	s_nop 2
	v_mul_f32_e64 v52, v78, v74
	v_mul_f32_e64 v53, v79, v75
	v_pk_mul_f32 v[50:51], v[206:207], v[74:75]
	v_pk_fma_f32 v[52:53], v[206:207], v[80:81], v[52:53]
	v_pk_fma_f32 v[50:51], v[78:79], v[80:81], v[50:51] neg_lo:[0,0,1] neg_hi:[0,0,1]
	v_pk_mul_f32 v[74:75], v[136:137], v[52:53]
	v_pk_mul_f32 v[80:81], v[72:73], v[52:53]
	v_pk_mul_f32 v[86:87], v[206:207], v[52:53]
	v_pk_mul_f32 v[52:53], v[78:79], v[52:53]
	v_pk_fma_f32 v[74:75], v[72:73], v[50:51], v[74:75] neg_lo:[0,0,1] neg_hi:[0,0,1]
	v_pk_fma_f32 v[80:81], v[136:137], v[50:51], v[80:81]
	v_pk_fma_f32 v[86:87], v[78:79], v[50:51], v[86:87] neg_lo:[0,0,1] neg_hi:[0,0,1]
	v_pk_fma_f32 v[50:51], v[206:207], v[50:51], v[52:53]
	s_nop 0
	v_pk_mul_f32 v[52:53], v[136:137], v[50:51]
	v_pk_mul_f32 v[50:51], v[72:73], v[50:51]
	v_pk_fma_f32 v[78:79], v[72:73], v[86:87], v[52:53] neg_lo:[0,0,1] neg_hi:[0,0,1]
	v_pk_mul_f32 v[52:53], v[82:83], v[76:77]
	v_pk_fma_f32 v[72:73], v[136:137], v[86:87], v[50:51]
	v_pk_mul_f32 v[50:51], v[210:211], v[76:77]
	v_pk_fma_f32 v[52:53], v[210:211], v[84:85], v[52:53]
	v_pk_fma_f32 v[50:51], v[82:83], v[84:85], v[50:51] neg_lo:[0,0,1] neg_hi:[0,0,1]
	v_pk_mul_f32 v[84:85], v[70:71], v[52:53]
	v_pk_mul_f32 v[76:77], v[116:117], v[52:53]
	v_pk_fma_f32 v[84:85], v[116:117], v[50:51], v[84:85]
	v_pk_mul_f32 v[86:87], v[210:211], v[52:53]
	v_pk_mul_f32 v[52:53], v[82:83], v[52:53]
	v_pk_fma_f32 v[76:77], v[70:71], v[50:51], v[76:77] neg_lo:[0,0,1] neg_hi:[0,0,1]
	v_pk_fma_f32 v[86:87], v[82:83], v[50:51], v[86:87] neg_lo:[0,0,1] neg_hi:[0,0,1]
	v_pk_fma_f32 v[82:83], v[210:211], v[50:51], v[52:53]
	v_cvt_pk_bf16_f32 v53, v77, v85
	v_cvt_pk_bf16_f32 v52, v76, v84
	v_cvt_pk_bf16_f32 v51, v75, v81
	v_cvt_pk_bf16_f32 v50, v74, v80
	s_nop 1
	v_mfma_f32_16x16x32_bf16 v[62:65], v[46:49], v[50:53], v[62:65]
	v_mul_f32_e64 v52, v70, v82
	v_mul_f32_e64 v53, v71, v83
	v_pk_mul_f32 v[50:51], v[116:117], v[82:83]
	v_pk_fma_f32 v[52:53], v[116:117], v[86:87], v[52:53]
	v_pk_fma_f32 v[50:51], v[70:71], v[86:87], v[50:51] neg_lo:[0,0,1] neg_hi:[0,0,1]
	s_nop 0
	v_cvt_pk_bf16_f32 v53, v51, v53
	v_cvt_pk_bf16_f32 v51, v79, v73
	v_cvt_pk_bf16_f32 v52, v50, v52
	v_cvt_pk_bf16_f32 v50, v78, v72
	s_waitcnt vmcnt(28)
	v_mov_b32_e32 v75, v198
	v_mov_b32_e32 v70, v42
	v_mov_b32_e32 v71, v44
	v_mov_b32_e32 v198, v203
	s_waitcnt vmcnt(24)
	v_mov_b32_e32 v77, v200
	v_mov_b32_e32 v72, v38
	v_mov_b32_e32 v73, v40
	v_mov_b32_e32 v200, v205
	v_mfma_f32_16x16x32_bf16 v[66:69], v[46:49], v[50:53], v[66:69]
	v_mov_b32_e32 v74, v202
	v_mov_b32_e32 v44, v43
	v_pk_mul_f32 v[46:47], v[198:199], v[70:71]
	v_mov_b32_e32 v76, v204
	v_mov_b32_e32 v40, v39
	v_pk_mul_f32 v[48:49], v[200:201], v[72:73]
	v_pk_mul_f32 v[42:43], v[198:199], v[44:45]
	v_pk_fma_f32 v[46:47], v[74:75], v[44:45], v[46:47]
	v_pk_mul_f32 v[38:39], v[200:201], v[40:41]
	v_pk_fma_f32 v[48:49], v[76:77], v[40:41], v[48:49]
	v_pk_fma_f32 v[42:43], v[74:75], v[70:71], v[42:43] neg_lo:[0,0,1] neg_hi:[0,0,1]
	v_pk_fma_f32 v[38:39], v[76:77], v[72:73], v[38:39] neg_lo:[0,0,1] neg_hi:[0,0,1]
	s_nop 0
	v_cvt_pk_bf16_f32 v49, v39, v49
	v_cvt_pk_bf16_f32 v48, v38, v48
	v_cvt_pk_bf16_f32 v47, v43, v47
	v_cvt_pk_bf16_f32 v46, v42, v46
	v_mov_b32_e32 v38, v192
	v_mov_b32_e32 v39, v190
	v_mov_b32_e32 v190, v193
	v_mfma_f32_16x16x32_bf16 v[50:53], v[34:37], v[46:49], v[54:57]
	v_mul_f32_e64 v42, v198, v190
	v_mul_f32_e64 v43, v199, v191
	v_pk_mul_f32 v[46:47], v[198:199], v[38:39]
	v_pk_fma_f32 v[42:43], v[74:75], v[38:39], v[42:43] neg_lo:[0,0,1] neg_hi:[0,0,1]
	v_mov_b32_e32 v56, v196
	s_waitcnt vmcnt(23)
	v_mov_b32_e32 v57, v194
	v_mov_b32_e32 v194, v197
	v_pk_fma_f32 v[54:55], v[74:75], v[190:191], v[46:47]
	v_pk_mul_f32 v[74:75], v[200:201], v[194:195]
	v_pk_mul_f32 v[78:79], v[200:201], v[56:57]
	v_pk_fma_f32 v[74:75], v[76:77], v[56:57], v[74:75] neg_lo:[0,0,1] neg_hi:[0,0,1]
	v_pk_fma_f32 v[76:77], v[76:77], v[194:195], v[78:79]
	v_pk_mul_f32 v[48:49], v[70:71], v[54:55]
	v_pk_mul_f32 v[80:81], v[72:73], v[76:77]
	v_pk_mul_f32 v[46:47], v[44:45], v[54:55]
	v_pk_fma_f32 v[48:49], v[44:45], v[42:43], v[48:49]
	v_pk_mul_f32 v[78:79], v[40:41], v[76:77]
	v_pk_fma_f32 v[80:81], v[40:41], v[74:75], v[80:81]
	v_pk_fma_f32 v[46:47], v[70:71], v[42:43], v[46:47] neg_lo:[0,0,1] neg_hi:[0,0,1]
	v_pk_fma_f32 v[78:79], v[72:73], v[74:75], v[78:79] neg_lo:[0,0,1] neg_hi:[0,0,1]
	v_cvt_pk_bf16_f32 v47, v47, v49
	v_cvt_pk_bf16_f32 v49, v79, v81
	v_cvt_pk_bf16_f32 v46, v46, v48
	v_cvt_pk_bf16_f32 v48, v78, v80
	s_nop 1
	v_mfma_f32_16x16x32_bf16 v[46:49], v[34:37], v[46:49], v[58:61]
	s_nop 2
	v_mul_f32_e64 v58, v190, v54
	v_mul_f32_e64 v59, v191, v55
	v_pk_mul_f32 v[54:55], v[38:39], v[54:55]
	v_pk_fma_f32 v[58:59], v[38:39], v[42:43], v[58:59] neg_lo:[0,0,1] neg_hi:[0,0,1]
	v_pk_fma_f32 v[42:43], v[190:191], v[42:43], v[54:55]
	s_nop 0
	v_pk_mul_f32 v[78:79], v[190:191], v[42:43]
	v_pk_mul_f32 v[54:55], v[44:45], v[42:43]
	v_pk_fma_f32 v[78:79], v[38:39], v[58:59], v[78:79] neg_lo:[0,0,1] neg_hi:[0,0,1]
	v_pk_mul_f32 v[38:39], v[38:39], v[42:43]
	v_pk_mul_f32 v[60:61], v[70:71], v[42:43]
	v_pk_fma_f32 v[38:39], v[190:191], v[58:59], v[38:39]
	v_pk_fma_f32 v[60:61], v[44:45], v[58:59], v[60:61]
	v_pk_mul_f32 v[42:43], v[44:45], v[38:39]
	v_pk_mul_f32 v[38:39], v[70:71], v[38:39]
	v_pk_fma_f32 v[54:55], v[70:71], v[58:59], v[54:55] neg_lo:[0,0,1] neg_hi:[0,0,1]
	v_pk_fma_f32 v[38:39], v[44:45], v[78:79], v[38:39]
	v_pk_mul_f32 v[44:45], v[56:57], v[76:77]
	v_pk_fma_f32 v[58:59], v[70:71], v[78:79], v[42:43] neg_lo:[0,0,1] neg_hi:[0,0,1]
	v_pk_mul_f32 v[42:43], v[194:195], v[76:77]
	v_pk_fma_f32 v[44:45], v[194:195], v[74:75], v[44:45]
	v_pk_fma_f32 v[42:43], v[56:57], v[74:75], v[42:43] neg_lo:[0,0,1] neg_hi:[0,0,1]
	v_pk_mul_f32 v[74:75], v[72:73], v[44:45]
	v_pk_mul_f32 v[70:71], v[40:41], v[44:45]
	v_pk_fma_f32 v[74:75], v[40:41], v[42:43], v[74:75]
	v_pk_mul_f32 v[76:77], v[194:195], v[44:45]
	v_pk_mul_f32 v[44:45], v[56:57], v[44:45]
	v_pk_fma_f32 v[70:71], v[72:73], v[42:43], v[70:71] neg_lo:[0,0,1] neg_hi:[0,0,1]
	v_pk_fma_f32 v[76:77], v[56:57], v[42:43], v[76:77] neg_lo:[0,0,1] neg_hi:[0,0,1]
	v_pk_fma_f32 v[56:57], v[194:195], v[42:43], v[44:45]
	v_cvt_pk_bf16_f32 v45, v71, v75
	v_cvt_pk_bf16_f32 v44, v70, v74
	v_cvt_pk_bf16_f32 v43, v55, v61
	v_cvt_pk_bf16_f32 v42, v54, v60
	v_pk_mul_f32 v[54:55], v[40:41], v[56:57]
	v_pk_mul_f32 v[56:57], v[72:73], v[56:57]
	v_pk_fma_f32 v[54:55], v[72:73], v[76:77], v[54:55] neg_lo:[0,0,1] neg_hi:[0,0,1]
	v_pk_fma_f32 v[40:41], v[40:41], v[76:77], v[56:57]
	v_cvt_pk_bf16_f32 v38, v58, v38
	v_cvt_pk_bf16_f32 v41, v55, v41
	v_cvt_pk_bf16_f32 v40, v54, v40
	v_cvt_pk_bf16_f32 v39, v59, v39
	s_waitcnt vmcnt(17)
	v_mov_b32_e32 v59, v182
	v_mov_b32_e32 v55, v32
	v_mov_b32_e32 v182, v185
	v_mov_b32_e32 v32, v31
	v_mov_b32_e32 v58, v184
	v_mov_b32_e32 v54, v30
	v_pk_mul_f32 v[30:31], v[182:183], v[32:33]
	v_mfma_f32_16x16x32_bf16 v[42:45], v[34:37], v[42:45], v[62:65]
	s_waitcnt vmcnt(13)
	v_mov_b32_e32 v57, v176
	v_mov_b32_e32 v176, v187
	v_mov_b32_e32 v56, v186
	v_mfma_f32_16x16x32_bf16 v[34:37], v[34:37], v[38:41], v[66:69]
	v_fma_f32 v38, v58, v54, -v30
	v_fma_f32 v39, v59, v55, -v31
	v_pk_mul_f32 v[30:31], v[182:183], v[54:55]
	s_nop 0
	v_pk_fma_f32 v[40:41], v[58:59], v[32:33], v[30:31]
	v_mov_b32_e32 v30, v22
	v_mov_b32_e32 v31, v24
	v_mov_b32_e32 v24, v23
	v_pk_mul_f32 v[60:61], v[176:177], v[30:31]
	v_pk_mul_f32 v[22:23], v[176:177], v[24:25]
	v_pk_fma_f32 v[60:61], v[56:57], v[24:25], v[60:61]
	v_pk_fma_f32 v[22:23], v[56:57], v[30:31], v[22:23] neg_lo:[0,0,1] neg_hi:[0,0,1]
	v_cvt_pk_bf16_f32 v39, v39, v41
	v_cvt_pk_bf16_f32 v41, v23, v61
	v_cvt_pk_bf16_f32 v38, v38, v40
	v_cvt_pk_bf16_f32 v40, v22, v60
	s_nop 1
	v_mfma_f32_16x16x32_bf16 v[38:41], v[14:17], v[38:41], v[50:53]
	s_nop 2
	v_mov_b32_e32 v51, v172
	v_mov_b32_e32 v172, v179
	v_mov_b32_e32 v50, v178
	v_pk_mul_f32 v[22:23], v[182:183], v[172:173]
	s_nop 0
	v_pk_fma_f32 v[52:53], v[58:59], v[50:51], v[22:23] neg_lo:[0,0,1] neg_hi:[0,0,1]
	v_pk_mul_f32 v[22:23], v[182:183], v[50:51]
	s_nop 0
	v_pk_fma_f32 v[58:59], v[58:59], v[172:173], v[22:23]
	s_nop 0
	v_pk_mul_f32 v[22:23], v[32:33], v[58:59]
	s_nop 0
	v_pk_fma_f32 v[60:61], v[54:55], v[52:53], v[22:23] neg_lo:[0,0,1] neg_hi:[0,0,1]
	v_pk_mul_f32 v[22:23], v[54:55], v[58:59]
	s_nop 0
	v_pk_fma_f32 v[62:63], v[32:33], v[52:53], v[22:23]
	v_mov_b32_e32 v22, v180
	s_waitcnt vmcnt(12)
	v_mov_b32_e32 v23, v170
	v_mov_b32_e32 v170, v181
	v_pk_mul_f32 v[64:65], v[176:177], v[170:171]
	v_pk_mul_f32 v[66:67], v[176:177], v[22:23]
	v_pk_fma_f32 v[64:65], v[56:57], v[22:23], v[64:65] neg_lo:[0,0,1] neg_hi:[0,0,1]
	v_pk_fma_f32 v[56:57], v[56:57], v[170:171], v[66:67]
	s_nop 0
	v_pk_mul_f32 v[68:69], v[30:31], v[56:57]
	v_pk_mul_f32 v[66:67], v[24:25], v[56:57]
	v_pk_fma_f32 v[68:69], v[24:25], v[64:65], v[68:69]
	v_pk_fma_f32 v[66:67], v[30:31], v[64:65], v[66:67] neg_lo:[0,0,1] neg_hi:[0,0,1]
	v_cvt_pk_bf16_f32 v61, v61, v63
	v_cvt_pk_bf16_f32 v63, v67, v69
	v_cvt_pk_bf16_f32 v60, v60, v62
	v_cvt_pk_bf16_f32 v62, v66, v68
	s_nop 1
	v_mfma_f32_16x16x32_bf16 v[46:49], v[14:17], v[60:63], v[46:49]
	v_mul_f32_e64 v60, v172, v58
	v_mul_f32_e64 v61, v173, v59
	v_pk_mul_f32 v[58:59], v[50:51], v[58:59]
	v_pk_fma_f32 v[60:61], v[50:51], v[52:53], v[60:61] neg_lo:[0,0,1] neg_hi:[0,0,1]
	v_pk_fma_f32 v[52:53], v[172:173], v[52:53], v[58:59]
	s_nop 0
	v_pk_mul_f32 v[66:67], v[172:173], v[52:53]
	v_pk_mul_f32 v[58:59], v[32:33], v[52:53]
	v_pk_fma_f32 v[66:67], v[50:51], v[60:61], v[66:67] neg_lo:[0,0,1] neg_hi:[0,0,1]
	v_pk_mul_f32 v[50:51], v[50:51], v[52:53]
	v_pk_mul_f32 v[62:63], v[54:55], v[52:53]
	v_pk_fma_f32 v[50:51], v[172:173], v[60:61], v[50:51]
	v_pk_fma_f32 v[58:59], v[54:55], v[60:61], v[58:59] neg_lo:[0,0,1] neg_hi:[0,0,1]
	v_pk_mul_f32 v[52:53], v[32:33], v[50:51]
	v_pk_fma_f32 v[62:63], v[32:33], v[60:61], v[62:63]
	v_pk_fma_f32 v[60:61], v[54:55], v[66:67], v[52:53] neg_lo:[0,0,1] neg_hi:[0,0,1]
	v_pk_mul_f32 v[50:51], v[54:55], v[50:51]
	v_pk_mul_f32 v[52:53], v[22:23], v[56:57]
	v_pk_fma_f32 v[32:33], v[32:33], v[66:67], v[50:51]
	v_pk_mul_f32 v[50:51], v[170:171], v[56:57]
	v_pk_fma_f32 v[52:53], v[170:171], v[64:65], v[52:53]
	v_pk_fma_f32 v[50:51], v[22:23], v[64:65], v[50:51] neg_lo:[0,0,1] neg_hi:[0,0,1]
	v_pk_mul_f32 v[56:57], v[30:31], v[52:53]
	v_pk_mul_f32 v[64:65], v[170:171], v[52:53]
	v_pk_mul_f32 v[54:55], v[24:25], v[52:53]
	v_pk_fma_f32 v[56:57], v[24:25], v[50:51], v[56:57]
	v_pk_fma_f32 v[64:65], v[22:23], v[50:51], v[64:65] neg_lo:[0,0,1] neg_hi:[0,0,1]
	v_pk_mul_f32 v[22:23], v[22:23], v[52:53]
	v_pk_fma_f32 v[54:55], v[30:31], v[50:51], v[54:55] neg_lo:[0,0,1] neg_hi:[0,0,1]
	v_pk_fma_f32 v[22:23], v[170:171], v[50:51], v[22:23]
	v_cvt_pk_bf16_f32 v53, v55, v57
	v_cvt_pk_bf16_f32 v52, v54, v56
	v_cvt_pk_bf16_f32 v51, v59, v63
	v_cvt_pk_bf16_f32 v50, v58, v62
	s_nop 1
	v_mfma_f32_16x16x32_bf16 v[42:45], v[14:17], v[50:53], v[42:45]
	v_mul_f32_e64 v50, v24, v22
	v_mul_f32_e64 v51, v25, v23
	v_pk_mul_f32 v[22:23], v[30:31], v[22:23]
	v_pk_fma_f32 v[50:51], v[30:31], v[64:65], v[50:51] neg_lo:[0,0,1] neg_hi:[0,0,1]
	v_pk_fma_f32 v[22:23], v[24:25], v[64:65], v[22:23]
	s_nop 0
	v_cvt_pk_bf16_f32 v25, v51, v23
	v_cvt_pk_bf16_f32 v23, v61, v33
	v_cvt_pk_bf16_f32 v24, v50, v22
	v_cvt_pk_bf16_f32 v22, v60, v32
	s_waitcnt vmcnt(7)
	v_mov_b32_e32 v50, v26
	v_mov_b32_e32 v51, v28
	v_mfma_f32_16x16x32_bf16 v[34:37], v[14:17], v[22:25], v[34:37]
	s_waitcnt vmcnt(6)
	v_mov_b32_e32 v23, v164
	v_mov_b32_e32 v164, v163
	v_mov_b32_e32 v28, v27
	s_waitcnt vmcnt(4)
	v_mov_b32_e32 v25, v174
	v_mov_b32_e32 v26, v18
	v_mov_b32_e32 v27, v20
	s_waitcnt vmcnt(3)
	v_mov_b32_e32 v174, v169
	v_mov_b32_e32 v22, v162
	v_pk_mul_f32 v[16:17], v[164:165], v[50:51]
	v_mov_b32_e32 v24, v168
	v_mov_b32_e32 v20, v19
	v_pk_mul_f32 v[30:31], v[174:175], v[26:27]
	v_pk_mul_f32 v[14:15], v[164:165], v[28:29]
	v_pk_fma_f32 v[16:17], v[22:23], v[28:29], v[16:17]
	v_pk_mul_f32 v[18:19], v[174:175], v[20:21]
	v_pk_fma_f32 v[30:31], v[24:25], v[20:21], v[30:31]
	v_pk_fma_f32 v[14:15], v[22:23], v[50:51], v[14:15] neg_lo:[0,0,1] neg_hi:[0,0,1]
	v_pk_fma_f32 v[18:19], v[24:25], v[26:27], v[18:19] neg_lo:[0,0,1] neg_hi:[0,0,1]
	v_cvt_pk_bf16_f32 v15, v15, v17
	v_cvt_pk_bf16_f32 v17, v19, v31
	v_cvt_pk_bf16_f32 v14, v14, v16
	v_cvt_pk_bf16_f32 v16, v18, v30
	v_mov_b32_e32 v19, v158
	v_mov_b32_e32 v158, v161
	v_mfma_f32_16x16x32_bf16 v[30:33], v[10:13], v[14:17], v[38:41]
	v_mov_b32_e32 v18, v160
	v_pk_mul_f32 v[14:15], v[164:165], v[158:159]
	s_waitcnt vmcnt(1)
	v_mov_b32_e32 v53, v188
	v_pk_fma_f32 v[38:39], v[22:23], v[18:19], v[14:15] neg_lo:[0,0,1] neg_hi:[0,0,1]
	v_pk_mul_f32 v[14:15], v[164:165], v[18:19]
	v_mov_b32_e32 v188, v167
	v_pk_fma_f32 v[40:41], v[22:23], v[158:159], v[14:15]
	v_mov_b32_e32 v52, v166
	v_pk_mul_f32 v[22:23], v[174:175], v[188:189]
	v_pk_mul_f32 v[16:17], v[50:51], v[40:41]
	v_pk_fma_f32 v[54:55], v[24:25], v[52:53], v[22:23] neg_lo:[0,0,1] neg_hi:[0,0,1]
	v_pk_mul_f32 v[22:23], v[174:175], v[52:53]
	v_pk_mul_f32 v[14:15], v[28:29], v[40:41]
	v_pk_fma_f32 v[56:57], v[24:25], v[188:189], v[22:23]
	v_pk_fma_f32 v[16:17], v[28:29], v[38:39], v[16:17]
	v_pk_mul_f32 v[24:25], v[26:27], v[56:57]
	v_pk_mul_f32 v[22:23], v[20:21], v[56:57]
	v_pk_fma_f32 v[24:25], v[20:21], v[54:55], v[24:25]
	v_pk_fma_f32 v[14:15], v[50:51], v[38:39], v[14:15] neg_lo:[0,0,1] neg_hi:[0,0,1]
	v_pk_fma_f32 v[22:23], v[26:27], v[54:55], v[22:23] neg_lo:[0,0,1] neg_hi:[0,0,1]
	v_cvt_pk_bf16_f32 v15, v15, v17
	v_cvt_pk_bf16_f32 v17, v23, v25
	v_cvt_pk_bf16_f32 v14, v14, v16
	v_cvt_pk_bf16_f32 v16, v22, v24
	s_nop 1
	v_mfma_f32_16x16x32_bf16 v[22:25], v[10:13], v[14:17], v[46:49]
	v_mul_f32_e64 v16, v18, v40
	v_mul_f32_e64 v17, v19, v41
	v_pk_mul_f32 v[14:15], v[158:159], v[40:41]
	v_pk_fma_f32 v[16:17], v[158:159], v[38:39], v[16:17]
	v_pk_fma_f32 v[14:15], v[18:19], v[38:39], v[14:15] neg_lo:[0,0,1] neg_hi:[0,0,1]
	v_pk_mul_f32 v[38:39], v[28:29], v[16:17]
	v_pk_mul_f32 v[40:41], v[50:51], v[16:17]
	v_pk_mul_f32 v[46:47], v[158:159], v[16:17]
	v_pk_mul_f32 v[16:17], v[18:19], v[16:17]
	v_pk_fma_f32 v[38:39], v[50:51], v[14:15], v[38:39] neg_lo:[0,0,1] neg_hi:[0,0,1]
	v_pk_fma_f32 v[40:41], v[28:29], v[14:15], v[40:41]
	v_pk_fma_f32 v[46:47], v[18:19], v[14:15], v[46:47] neg_lo:[0,0,1] neg_hi:[0,0,1]
	v_pk_fma_f32 v[14:15], v[158:159], v[14:15], v[16:17]
	s_nop 0
	v_pk_mul_f32 v[16:17], v[28:29], v[14:15]
	v_pk_mul_f32 v[14:15], v[50:51], v[14:15]
	v_pk_fma_f32 v[18:19], v[50:51], v[46:47], v[16:17] neg_lo:[0,0,1] neg_hi:[0,0,1]
	v_pk_mul_f32 v[16:17], v[52:53], v[56:57]
	v_pk_fma_f32 v[28:29], v[28:29], v[46:47], v[14:15]
	v_pk_mul_f32 v[14:15], v[188:189], v[56:57]
	v_pk_fma_f32 v[16:17], v[188:189], v[54:55], v[16:17]
	v_pk_fma_f32 v[14:15], v[52:53], v[54:55], v[14:15] neg_lo:[0,0,1] neg_hi:[0,0,1]
	v_pk_mul_f32 v[48:49], v[26:27], v[16:17]
	v_pk_mul_f32 v[46:47], v[20:21], v[16:17]
	v_pk_fma_f32 v[48:49], v[20:21], v[14:15], v[48:49]
	v_pk_mul_f32 v[50:51], v[188:189], v[16:17]
	v_pk_mul_f32 v[16:17], v[52:53], v[16:17]
	v_pk_fma_f32 v[46:47], v[26:27], v[14:15], v[46:47] neg_lo:[0,0,1] neg_hi:[0,0,1]
	v_pk_fma_f32 v[50:51], v[52:53], v[14:15], v[50:51] neg_lo:[0,0,1] neg_hi:[0,0,1]
	v_pk_fma_f32 v[52:53], v[188:189], v[14:15], v[16:17]
	v_cvt_pk_bf16_f32 v17, v47, v49
	v_cvt_pk_bf16_f32 v16, v46, v48
	v_cvt_pk_bf16_f32 v15, v39, v41
	v_cvt_pk_bf16_f32 v14, v38, v40
	v_pk_mul_f32 v[38:39], v[20:21], v[52:53]
	s_nop 0
	v_pk_fma_f32 v[38:39], v[26:27], v[50:51], v[38:39] neg_lo:[0,0,1] neg_hi:[0,0,1]
	v_pk_mul_f32 v[26:27], v[26:27], v[52:53]
	s_nop 0
	v_pk_fma_f32 v[20:21], v[20:21], v[50:51], v[26:27]
	v_cvt_pk_bf16_f32 v19, v19, v29
	v_cvt_pk_bf16_f32 v18, v18, v28
	v_cvt_pk_bf16_f32 v21, v39, v21
	v_cvt_pk_bf16_f32 v20, v38, v20
	v_mfma_f32_16x16x32_bf16 v[14:17], v[10:13], v[14:17], v[42:45]
	v_mov_b32_e32 v29, v32
	v_mov_b32_e32 v32, v31
	v_mov_b32_e32 v28, v30
	v_mfma_f32_16x16x32_bf16 v[10:13], v[10:13], v[18:21], v[34:37]
	s_waitcnt vmcnt(0)
	v_mov_b32_e32 v19, v8
	v_mov_b32_e32 v8, v7
	v_mov_b32_e32 v18, v6
	v_add_u32_e32 v34, s22, v242
	ds_read_b64 v[20:21], v34
	v_add_u32_e32 v242, 32, v242
	s_waitcnt lgkmcnt(0)
	v_lshlrev_b32_e32 v27, 16, v21
	v_lshlrev_b32_e32 v26, 16, v20
	v_and_b32_e32 v21, 0xffff0000, v21
	v_and_b32_e32 v20, 0xffff0000, v20
	v_pk_fma_f32 v[20:21], v[8:9], v[20:21], v[32:33]
	v_pk_fma_f32 v[26:27], v[18:19], v[26:27], v[28:29]
	v_mul_f32_e32 v7, 0x3d372713, v20
	v_mul_f32_e32 v7, v20, v7
	v_fma_f32 v7, v20, v7, v20
	v_mul_f32_e32 v7, 0x3f4c422a, v7
	v_mul_f32_e32 v7, -2.0, v7
	v_mul_f32_e32 v7, 0x3fb8aa3b, v7
	v_exp_f32_e32 v7, v7
	v_mul_f32_e32 v6, 0x3d372713, v26
	v_mul_f32_e32 v6, v26, v6
	v_fma_f32 v6, v26, v6, v26
	v_add_f32_e32 v7, 1.0, v7
	v_rcp_f32_e32 v28, v7
	v_mul_f32_e32 v7, 0x3d372713, v27
	v_mul_f32_e32 v7, v27, v7
	v_fma_f32 v7, v27, v7, v27
	v_mul_f32_e32 v6, 0x3f4c422a, v6
	v_mul_f32_e32 v7, 0x3f4c422a, v7
	v_mul_f32_e32 v6, -2.0, v6
	v_mul_f32_e32 v7, -2.0, v7
	v_mul_f32_e32 v6, 0x3fb8aa3b, v6
	v_mul_f32_e32 v7, 0x3fb8aa3b, v7
	v_exp_f32_e32 v6, v6
	v_exp_f32_e32 v7, v7
	v_add_f32_e32 v6, 1.0, v6
	v_add_f32_e32 v7, 1.0, v7
	v_rcp_f32_e32 v6, v6
	v_rcp_f32_e32 v7, v7
	s_nop 0
	v_pk_mul_f32 v[6:7], v[26:27], v[6:7]
	v_mul_f32_e32 v26, 0x3d372713, v21
	v_mul_f32_e32 v26, v21, v26
	v_fma_f32 v26, v21, v26, v21
	v_mul_f32_e32 v26, 0x3f4c422a, v26
	v_mul_f32_e32 v26, -2.0, v26
	v_mul_f32_e32 v26, 0x3fb8aa3b, v26
	v_exp_f32_e32 v26, v26
	s_nop 0
	v_add_f32_e32 v26, 1.0, v26
	v_rcp_f32_e32 v29, v26
	s_nop 0
	v_pk_mul_f32 v[20:21], v[20:21], v[28:29]
	s_nop 0
	v_cvt_pk_bf16_f32 v6, v6, v20
	v_cvt_pk_bf16_f32 v7, v7, v21
	ds_write_b64 v34, v[6:7]
	v_add_u32_e32 v28, s22, v241
	ds_read_b64 v[6:7], v28 offset:33280
	v_mov_b32_e32 v27, v24
	v_mov_b32_e32 v24, v23
	v_mov_b32_e32 v26, v22
	v_add_u32_e32 v241, 32, v241
	s_waitcnt lgkmcnt(0)
	v_lshlrev_b32_e32 v21, 16, v7
	v_lshlrev_b32_e32 v20, 16, v6
	v_and_b32_e32 v7, 0xffff0000, v7
	v_and_b32_e32 v6, 0xffff0000, v6
	v_pk_fma_f32 v[6:7], v[8:9], v[6:7], v[24:25]
	v_pk_fma_f32 v[20:21], v[18:19], v[20:21], v[26:27]
	v_mul_f32_e32 v23, 0x3d372713, v6
	v_mul_f32_e32 v23, v6, v23
	v_fma_f32 v23, v6, v23, v6
	v_mul_f32_e32 v23, 0x3f4c422a, v23
	v_mul_f32_e32 v23, -2.0, v23
	v_mul_f32_e32 v23, 0x3fb8aa3b, v23
	v_exp_f32_e32 v23, v23
	v_mul_f32_e32 v22, 0x3d372713, v20
	v_mul_f32_e32 v22, v20, v22
	v_fma_f32 v22, v20, v22, v20
	v_add_f32_e32 v23, 1.0, v23
	v_rcp_f32_e32 v24, v23
	v_mul_f32_e32 v23, 0x3d372713, v21
	v_mul_f32_e32 v23, v21, v23
	v_fma_f32 v23, v21, v23, v21
	v_mul_f32_e32 v22, 0x3f4c422a, v22
	v_mul_f32_e32 v23, 0x3f4c422a, v23
	v_mul_f32_e32 v22, -2.0, v22
	v_mul_f32_e32 v23, -2.0, v23
	v_mul_f32_e32 v22, 0x3fb8aa3b, v22
	v_mul_f32_e32 v23, 0x3fb8aa3b, v23
	v_exp_f32_e32 v22, v22
	v_exp_f32_e32 v23, v23
	v_add_f32_e32 v22, 1.0, v22
	v_add_f32_e32 v23, 1.0, v23
	v_rcp_f32_e32 v22, v22
	v_rcp_f32_e32 v23, v23
	s_nop 0
	v_pk_mul_f32 v[20:21], v[20:21], v[22:23]
	v_mul_f32_e32 v22, 0x3d372713, v7
	v_mul_f32_e32 v22, v7, v22
	v_fma_f32 v22, v7, v22, v7
	v_mul_f32_e32 v22, 0x3f4c422a, v22
	v_mul_f32_e32 v22, -2.0, v22
	v_mul_f32_e32 v22, 0x3fb8aa3b, v22
	v_exp_f32_e32 v22, v22
	s_nop 0
	v_add_f32_e32 v22, 1.0, v22
	v_rcp_f32_e32 v25, v22
	s_nop 0
	v_pk_mul_f32 v[6:7], v[6:7], v[24:25]
	s_nop 0
	v_cvt_pk_bf16_f32 v6, v20, v6
	v_cvt_pk_bf16_f32 v7, v21, v7
	ds_write_b64 v28, v[6:7] offset:33280
	ds_read_b64 v[6:7], v28 offset:49920
	v_mov_b32_e32 v23, v16
	v_mov_b32_e32 v16, v15
	v_mov_b32_e32 v22, v14
	s_waitcnt lgkmcnt(0)
	v_lshlrev_b32_e32 v21, 16, v7
	v_lshlrev_b32_e32 v20, 16, v6
	v_and_b32_e32 v7, 0xffff0000, v7
	v_and_b32_e32 v6, 0xffff0000, v6
	v_pk_fma_f32 v[6:7], v[8:9], v[6:7], v[16:17]
	v_pk_fma_f32 v[20:21], v[18:19], v[20:21], v[22:23]
	v_mul_f32_e32 v15, 0x3d372713, v6
	v_mul_f32_e32 v15, v6, v15
	v_fma_f32 v15, v6, v15, v6
	v_mul_f32_e32 v15, 0x3f4c422a, v15
	v_mul_f32_e32 v15, -2.0, v15
	v_mul_f32_e32 v15, 0x3fb8aa3b, v15
	v_exp_f32_e32 v15, v15
	v_mul_f32_e32 v14, 0x3d372713, v20
	v_mul_f32_e32 v14, v20, v14
	v_mul_f32_e32 v17, 0x3d372713, v7
	v_add_f32_e32 v15, 1.0, v15
	v_rcp_f32_e32 v16, v15
	v_mul_f32_e32 v15, 0x3d372713, v21
	v_mul_f32_e32 v15, v21, v15
	v_fma_f32 v14, v20, v14, v20
	v_fma_f32 v15, v21, v15, v21
	v_mul_f32_e32 v17, v7, v17
	v_mul_f32_e32 v14, 0x3f4c422a, v14
	v_mul_f32_e32 v15, 0x3f4c422a, v15
	v_fma_f32 v17, v7, v17, v7
	v_mul_f32_e32 v14, -2.0, v14
	v_mul_f32_e32 v15, -2.0, v15
	v_mul_f32_e32 v17, 0x3f4c422a, v17
	v_mul_f32_e32 v14, 0x3fb8aa3b, v14
	v_mul_f32_e32 v15, 0x3fb8aa3b, v15
	v_mul_f32_e32 v17, -2.0, v17
	v_exp_f32_e32 v14, v14
	v_exp_f32_e32 v15, v15
	v_mul_f32_e32 v17, 0x3fb8aa3b, v17
	v_exp_f32_e32 v17, v17
	v_add_f32_e32 v14, 1.0, v14
	v_add_f32_e32 v15, 1.0, v15
	v_rcp_f32_e32 v14, v14
	v_rcp_f32_e32 v15, v15
	v_add_f32_e32 v17, 1.0, v17
	v_rcp_f32_e32 v17, v17
	v_pk_mul_f32 v[14:15], v[20:21], v[14:15]
	v_add_u32_e32 v20, 0x10400, v28
	v_pk_mul_f32 v[6:7], v[6:7], v[16:17]
	s_nop 0
	v_cvt_pk_bf16_f32 v7, v15, v7
	v_cvt_pk_bf16_f32 v6, v14, v6
	ds_write_b64 v28, v[6:7] offset:49920
	ds_read_b64 v[6:7], v20
	v_mov_b32_e32 v16, v10
	v_mov_b32_e32 v17, v12
	v_mov_b32_e32 v12, v11
	s_waitcnt lgkmcnt(0)
	v_lshlrev_b32_e32 v15, 16, v7
	v_lshlrev_b32_e32 v14, 16, v6
	v_pk_fma_f32 v[14:15], v[18:19], v[14:15], v[16:17]
	v_and_b32_e32 v7, 0xffff0000, v7
	v_and_b32_e32 v6, 0xffff0000, v6
	v_pk_fma_f32 v[6:7], v[8:9], v[6:7], v[12:13]
	v_mul_f32_e32 v9, 0x3d372713, v15
	v_mul_f32_e32 v9, v15, v9
	v_fma_f32 v9, v15, v9, v15
	v_mul_f32_e32 v9, 0x3f4c422a, v9
	v_mul_f32_e32 v9, -2.0, v9
	v_mul_f32_e32 v9, 0x3fb8aa3b, v9
	v_exp_f32_e32 v9, v9
	v_mul_f32_e32 v10, 0x3d372713, v14
	v_mul_f32_e32 v10, v14, v10
	v_mul_f32_e32 v8, 0x3d372713, v6
	v_add_f32_e32 v9, 1.0, v9
	v_rcp_f32_e32 v11, v9
	v_mul_f32_e32 v9, 0x3d372713, v7
	v_fma_f32 v10, v14, v10, v14
	v_mul_f32_e32 v8, v6, v8
	v_mul_f32_e32 v9, v7, v9
	v_mul_f32_e32 v10, 0x3f4c422a, v10
	v_fma_f32 v8, v6, v8, v6
	v_fma_f32 v9, v7, v9, v7
	v_mul_f32_e32 v10, -2.0, v10
	v_mul_f32_e32 v8, 0x3f4c422a, v8
	v_mul_f32_e32 v9, 0x3f4c422a, v9
	v_mul_f32_e32 v10, 0x3fb8aa3b, v10
	v_mul_f32_e32 v8, -2.0, v8
	v_mul_f32_e32 v9, -2.0, v9
	v_exp_f32_e32 v10, v10
	v_mul_f32_e32 v8, 0x3fb8aa3b, v8
	v_mul_f32_e32 v9, 0x3fb8aa3b, v9
	v_exp_f32_e32 v8, v8
	v_exp_f32_e32 v9, v9
	v_add_f32_e32 v10, 1.0, v10
	v_rcp_f32_e32 v10, v10
	v_add_f32_e32 v8, 1.0, v8
	v_add_f32_e32 v9, 1.0, v9
	v_rcp_f32_e32 v8, v8
	v_rcp_f32_e32 v9, v9
	v_pk_mul_f32 v[10:11], v[14:15], v[10:11]
	v_pk_mul_f32 v[6:7], v[6:7], v[8:9]
	s_nop 0
	v_cvt_pk_bf16_f32 v7, v11, v7
	v_cvt_pk_bf16_f32 v6, v10, v6
	ds_write_b64 v20, v[6:7]
	s_cbranch_scc0 .LBB0_464
	s_and_b32 s0, s20, 0xffffffc0
	v_or_b32_e32 v6, s0, v1
	v_ashrrev_i32_e32 v7, 31, v6
	v_readlane_b32 s4, v254, 8
	v_lshlrev_b64 v[10:11], 10, v[6:7]
	v_readlane_b32 s5, v254, 9
	s_ashr_i32 s1, s0, 31
	v_readlane_b32 s6, v254, 10
	v_lshl_add_u64 v[6:7], s[4:5], 0, v[10:11]
	s_nop 1
	s_mov_b64 s[36:37], s[4:5]
	s_add_u32 s38, s4, 0x4000
	s_addc_u32 s39, s5, 0
	s_add_u32 s40, s4, 0x8000
	s_addc_u32 s41, s5, 0
	s_add_u32 s44, s4, 0xc000
	s_addc_u32 s45, s5, 0
	s_lshl_b64 s[4:5], s[0:1], 2
	s_add_u32 s4, s6, s4
	v_readlane_b32 s6, v254, 11
	s_addc_u32 s5, s6, s5
	v_readlane_b32 s6, v251, 55
	v_lshlrev_b32_e32 v12, 1, v238
	v_add_u32_e32 v239, v10, v12
	v_mov_b32_e32 v13, v139
	v_readlane_b32 s7, v251, 56
	v_lshl_add_u64 v[136:137], v[6:7], 0, v[12:13]
	v_or_b32_e32 v22, s88, v1
	v_mov_b64_e32 v[6:7], s[6:7]
	s_movk_i32 s10, 0x2800
	v_mad_i64_i32 v[134:135], s[6:7], v22, s10, v[6:7]
	s_lshl_b64 s[6:7], s[0:1], 1
	s_nop 0
	v_lshl_add_u64 v[8:9], v[134:135], 0, s[6:7]
	v_lshlrev_b32_e32 v14, 1, v146
	v_mov_b32_e32 v15, v139
	v_lshl_add_u64 v[16:17], v[8:9], 0, v[14:15]
	v_or_b32_e32 v8, 16, v22
	v_mad_i64_i32 v[8:9], s[8:9], v8, s10, v[6:7]
	v_lshl_add_u64 v[8:9], v[8:9], 0, s[6:7]
	v_lshl_add_u64 v[18:19], v[8:9], 0, v[14:15]
	v_or_b32_e32 v8, 32, v22
	v_mad_i64_i32 v[8:9], s[8:9], v8, s10, v[6:7]
	v_lshl_add_u64 v[8:9], v[8:9], 0, s[6:7]
	v_lshl_add_u64 v[20:21], v[8:9], 0, v[14:15]
	v_or_b32_e32 v8, 48, v22
	v_mad_i64_i32 v[6:7], s[8:9], v8, s10, v[6:7]
	v_lshl_add_u64 v[6:7], v[6:7], 0, s[6:7]
	v_lshl_add_u64 v[14:15], v[6:7], 0, v[14:15]
	v_add_co_u32_e32 v6, vcc, s69, v136
	v_lshlrev_b32_e32 v13, 2, v146
	s_nop 0
	v_addc_co_u32_e32 v7, vcc, 0, v137, vcc
	v_add_co_u32_e32 v8, vcc, s19, v136
	s_nop 0
	s_nop 0
	v_addc_co_u32_e32 v9, vcc, 0, v137, vcc
	s_nop 0
	s_nop 0
	s_nop 0
	s_nop 0
	v_add_co_u32_e32 v6, vcc, s27, v136
	v_add_u32_e32 v150, 0, v237
	s_nop 0
	v_addc_co_u32_e32 v7, vcc, 0, v137, vcc
	s_nop 0
	s_nop 0
	s_nop 0
	s_nop 0
	v_lshlrev_b32_e32 v220, 2, v146
	s_mov_b64 s[46:47], s[4:5]
	global_load_dwordx4 v[74:77], v239, s[36:37] offset:0
	global_load_dwordx4 v[140:143], v239, s[36:37] offset:64
	global_load_dwordx4 v[96:99], v239, s[38:39] offset:0
	global_load_dwordx4 v[152:155], v239, s[38:39] offset:64
	global_load_dwordx4 v[92:95], v239, s[40:41] offset:0
	global_load_dwordx4 v[156:159], v239, s[40:41] offset:64
	global_load_dwordx4 v[88:91], v239, s[44:45] offset:0
	global_load_dwordx4 v[160:163], v239, s[44:45] offset:64
	global_load_dwordx4 v[180:183], v239, s[36:37] offset:128
	global_load_dwordx4 v[196:199], v239, s[36:37] offset:192
	global_load_dwordx4 v[184:187], v239, s[38:39] offset:128
	global_load_dwordx4 v[200:203], v239, s[38:39] offset:192
	global_load_dwordx4 v[188:191], v239, s[40:41] offset:128
	global_load_dwordx4 v[204:207], v239, s[40:41] offset:192
	global_load_dwordx4 v[192:195], v239, s[44:45] offset:128
	global_load_dwordx4 v[208:211], v239, s[44:45] offset:192
	global_load_dwordx4 v[212:215], v239, s[36:37] offset:256
	global_load_dwordx4 v[66:69], v239, s[36:37] offset:320
	global_load_dwordx4 v[216:219], v239, s[38:39] offset:256
	global_load_dwordx4 v[46:49], v239, s[38:39] offset:320
	global_load_dwordx4 v[240:243], v239, s[40:41] offset:256
	global_load_dwordx4 v[26:29], v239, s[40:41] offset:320
	global_load_dwordx4 v[244:247], v239, s[44:45] offset:256
	global_load_dwordx4 v[6:9], v239, s[44:45] offset:320
	global_load_dwordx2 v[78:79], v[16:17], off offset:2560
	global_load_dwordx2 v[126:127], v[16:17], off offset:2592
	global_load_dwordx2 v[118:119], v[16:17], off offset:2624
	global_load_dwordx2 v[110:111], v[16:17], off offset:2656
	global_load_dwordx2 v[132:133], v[18:19], off offset:2560
	global_load_dwordx2 v[124:125], v[18:19], off offset:2592
	global_load_dwordx2 v[116:117], v[18:19], off offset:2624
	global_load_dwordx2 v[108:109], v[18:19], off offset:2656
	global_load_dwordx2 v[130:131], v[20:21], off offset:2560
	global_load_dwordx2 v[122:123], v[20:21], off offset:2592
	global_load_dwordx2 v[114:115], v[20:21], off offset:2624
	global_load_dwordx2 v[106:107], v[20:21], off offset:2656
	global_load_dwordx2 v[128:129], v[14:15], off offset:2560
	global_load_dwordx2 v[120:121], v[14:15], off offset:2592
	global_load_dwordx2 v[112:113], v[14:15], off offset:2624
	global_load_dwordx2 v[104:105], v[14:15], off offset:2656
	v_readlane_b32 s4, v254, 61
	v_or_b32_e32 v10, v10, v138
	v_readlane_b32 s5, v254, 62
	v_mov_b32_e32 v30, 0
	v_add_u32_e32 v151, v150, v12
	v_lshl_add_u64 v[148:149], s[4:5], 0, v[10:11]
	s_mov_b64 s[22:23], 0
	s_mov_b32 s1, 64
	v_mov_b32_e32 v31, v30
	v_mov_b32_e32 v32, v30
	v_mov_b32_e32 v33, v30
	v_mov_b32_e32 v34, v30
	v_mov_b32_e32 v35, v30
	v_mov_b32_e32 v36, v30
	v_mov_b32_e32 v37, v30
	v_mov_b32_e32 v38, v30
	v_mov_b32_e32 v39, v30
	v_mov_b32_e32 v40, v30
	v_mov_b32_e32 v41, v30
	v_mov_b32_e32 v42, v30
	v_mov_b32_e32 v43, v30
	v_mov_b32_e32 v44, v30
	v_mov_b32_e32 v45, v30
	v_mov_b32_e32 v50, v30
	v_mov_b32_e32 v51, v30
	v_mov_b32_e32 v52, v30
	v_mov_b32_e32 v53, v30
	v_mov_b32_e32 v54, v30
	v_mov_b32_e32 v55, v30
	v_mov_b32_e32 v56, v30
	v_mov_b32_e32 v57, v30
	v_mov_b32_e32 v58, v30
	v_mov_b32_e32 v59, v30
	v_mov_b32_e32 v60, v30
	v_mov_b32_e32 v61, v30
	v_mov_b32_e32 v62, v30
	v_mov_b32_e32 v63, v30
	v_mov_b32_e32 v64, v30
	v_mov_b32_e32 v65, v30
	v_mov_b32_e32 v70, v30
	v_mov_b32_e32 v71, v30
	v_mov_b32_e32 v72, v30
	v_mov_b32_e32 v73, v30
	v_mov_b32_e32 v84, v30
	v_mov_b32_e32 v85, v30
	v_mov_b32_e32 v86, v30
	v_mov_b32_e32 v87, v30
	v_mov_b32_e32 v80, v30
	v_mov_b32_e32 v81, v30
	v_mov_b32_e32 v82, v30
	v_mov_b32_e32 v83, v30
	v_mov_b32_e32 v100, v30
	v_mov_b32_e32 v101, v30
	v_mov_b32_e32 v102, v30
	v_mov_b32_e32 v103, v30
	v_mov_b32_e32 v22, v30
	v_mov_b32_e32 v23, v30
	v_mov_b32_e32 v24, v30
	v_mov_b32_e32 v25, v30
	v_mov_b32_e32 v18, v30
	v_mov_b32_e32 v19, v30
	v_mov_b32_e32 v20, v30
	v_mov_b32_e32 v21, v30
	v_mov_b32_e32 v14, v30
	v_mov_b32_e32 v15, v30
	v_mov_b32_e32 v16, v30
	v_mov_b32_e32 v17, v30
	v_mov_b32_e32 v10, v30
	v_mov_b32_e32 v11, v30
	v_mov_b32_e32 v12, v30
	v_mov_b32_e32 v13, v30
	s_waitcnt lgkmcnt(0)
	s_barrier

.Lp0_tables_entry:
	v_readlane_b32 s0, v250, 14
	v_readlane_b32 s12, v252, 51
	v_mov_b32_e32 v114, v0
	v_readlane_b32 s1, v250, 15
	v_readlane_b32 s13, v252, 52
	v_readlane_b32 s14, v250, 27
	v_readlane_b32 s52, v253, 26
	s_andn2_b64 vcc, exec, s[0:1]
	v_readfirstlane_b32 s20, v114
	v_readlane_b32 s48, v250, 2
	v_readlane_b32 s11, v250, 25
	v_readlane_b32 s13, v250, 26
	v_readlane_b32 s15, v250, 28
	v_readlane_b32 s10, v252, 38
	v_readlane_b32 s16, v252, 18
	v_readlane_b32 s88, v252, 19
	v_readlane_b32 s51, v252, 20
	v_readlane_b32 s89, v252, 21
	v_readlane_b32 s56, v253, 30
	v_readlane_b32 s57, v253, 31
	v_readlane_b32 s53, v253, 27
	v_readlane_b32 s54, v253, 28
	v_readlane_b32 s55, v253, 29
	v_readlane_b32 s58, v253, 32
	v_readlane_b32 s59, v253, 33
	v_readlane_b32 s60, v253, 34
	v_readlane_b32 s61, v253, 35
	v_readlane_b32 s62, v253, 36
	v_readlane_b32 s63, v253, 37
	v_readlane_b32 s64, v253, 38
	v_readlane_b32 s65, v253, 39
	v_readlane_b32 s66, v253, 40
	v_readlane_b32 s67, v253, 41
	v_readlane_b32 s98, v255, 62
	s_bitcmp1_b32 s48, 0
	s_cbranch_scc0 .Lp0_tab_go
	s_cmp_eq_u32 s98, 0
	s_cbranch_scc1 .LBB0_766
.Lp0_tab_go:
	s_cbranch_vccnz .LBB0_766

.LBB0_766:
	v_readlane_b32 s98, v255, 62
	s_nop 3
	s_cmp_eq_u32 s98, 1
	s_cbranch_scc1 .Lp0_late_done
	v_readlane_b32 s0, v250, 18
	s_nop 1
	v_add_u32_e32 v6, s0, v114
	s_mov_b32 s0, 0x40000
	v_cmp_gt_i32_e32 vcc, s0, v6
	s_and_saveexec_b64 s[2:3], vcc
	v_readlane_b32 s4, v252, 55
	v_readlane_b32 s28, v250, 22
	v_readlane_b32 s5, v252, 56
	s_cbranch_execz .LBB0_774
	s_waitcnt lgkmcnt(0)
	v_add_u32_e32 v1, s4, v6
	s_waitcnt lgkmcnt(0)
	v_max_i32_e32 v7, 0x40000, v1
	v_cmp_gt_i32_e32 vcc, s0, v1
	s_mov_b64 s[0:1], -1
	s_nop 0
	v_cndmask_b32_e64 v8, 1, 2, vcc
	v_subb_co_u32_e32 v1, vcc, v7, v1, vcc
	v_mul_hi_u32 v7, v1, v222
	v_mul_lo_u32 v9, v7, s4
	v_sub_u32_e32 v1, v1, v9
	v_add_u32_e32 v9, 1, v7
	v_cmp_le_u32_e32 vcc, s4, v1
	s_nop 1
	v_cndmask_b32_e32 v7, v7, v9, vcc
	v_subrev_u32_e32 v9, s4, v1
	v_cndmask_b32_e32 v1, v1, v9, vcc
	v_add_u32_e32 v9, 1, v7
	v_cmp_le_u32_e32 vcc, s4, v1
	s_nop 1
	v_cndmask_b32_e32 v1, v7, v9, vcc
	v_add_u32_e32 v9, v8, v1
	v_cmp_lt_u32_e32 vcc, 1, v9
	s_and_saveexec_b64 s[22:23], vcc
	s_cbranch_execz .LBB0_771
	v_readlane_b32 s0, v251, 43
	v_and_b32_e32 v10, -2, v9
	v_readlane_b32 s1, v251, 44
	v_readlane_b32 s4, v250, 19
	v_add_u32_e32 v8, s0, v6
	v_add_u32_e32 v1, s1, v6
	s_mov_b64 s[24:25], 0
	v_mov_b32_e32 v7, v10
	v_readlane_b32 s5, v250, 20

.LBB0_860:
.LBB0_861:
	v_readlane_b32 s98, v255, 62
	v_readlane_b32 s99, v250, 2
	s_nop 3
	s_cmp_lg_u32 s98, 0
	s_cbranch_scc1 .Lp0_end_orig
	s_bitcmp1_b32 s99, 0
	s_cbranch_scc0 .Lp0_end_orig
	s_nop 1
	v_writelane_b32 v255, s28, 10
	v_writelane_b32 v255, s29, 11
	v_writelane_b32 v255, s30, 12
	v_writelane_b32 v255, s31, 13
	v_writelane_b32 v255, s34, 14
	v_writelane_b32 v255, s35, 15
	v_writelane_b32 v255, s88, 16
	s_mov_b32 s98, 1
	s_nop 1
	v_writelane_b32 v255, s98, 62
	s_waitcnt vmcnt(0) lgkmcnt(0)
	s_barrier
	s_branch .Lp0_tables_entry
.Lp0_late_done:
	v_readlane_b32 s28, v255, 10
	v_readlane_b32 s29, v255, 11
	v_readlane_b32 s30, v255, 12
	v_readlane_b32 s31, v255, 13
	v_readlane_b32 s34, v255, 14
	v_readlane_b32 s35, v255, 15
	v_readlane_b32 s88, v255, 16
	s_mov_b32 s98, 2
	s_nop 1
	v_writelane_b32 v255, s98, 62
.Lp0_end_orig:
	v_readlane_b32 s50, v253, 48
	v_readlane_b32 s52, v253, 50
	v_readlane_b32 s51, v253, 49
	s_branch .LBB0_862
.LBB0_862:
	v_readlane_b32 s0, v250, 6
	v_readlane_b32 s2, v250, 8
	v_readlane_b32 s1, v250, 7
	v_readlane_b32 s3, v250, 9
	s_add_i32 s2, s2, 1
	v_writelane_b32 v250, s0, 6
	s_cmp_ge_i32 s2, s3
	s_nop 0
	v_writelane_b32 v250, s1, 7
	v_writelane_b32 v250, s2, 8
	v_writelane_b32 v250, s3, 9
	s_mov_b64 s[0:1], -1
	s_cbranch_scc0 .LBB0_863
	s_getpc_b64 s[98:99]
